# per-path vmcnt in DSA stage3 + band step loops (keep next-step K/V loads in flight) + L2 touch-prefetch of Y rows in residual epilogues
# baseline (speedup 1.0000x reference)
; __device__ __forceinline__ float xsum16(float v) { const auto r = __builtin_amdgcn_permlane16_swap(__float_as_uint(v), __float_as_uint(v), false, false); return __uint_as_float(r[0]) + __uint_as_float(r[1]); }
; __device__ __forceinline__ float xsum32(float v) { const auto r = __builtin_amdgcn_permlane32_swap(__float_as_uint(v), __float_as_uint(v), false, false); return __uint_as_float(r[0]) + __uint_as_float(r[1]); }
; __device__ __forceinline__ void row_stats4(const float* st, int rowb, int fq, float (&mu)[4], float (&rs)[4]) {
;     f32x4 a[4], b[4];
; #pragma unroll
;     for (int m = 0; m < 4; ++m) { const f32x4* p = (const f32x4*)(st + (size_t)(rowb + m * 16) * 32 + fq * 8); a[m] = p[0]; b[m] = p[1]; }
; #pragma unroll
;     for (int m = 0; m < 4; ++m) { float s1 = (a[m][0] + a[m][2]) + (b[m][0] + b[m][2]), s2 = (a[m][1] + a[m][3]) + (b[m][1] + b[m][3]);
;         s1 = xsum32(xsum16(s1)); s2 = xsum32(xsum16(s2));
;         const float mm = s1 * (1.0f / 1024.0f); mu[m] = mm; rs[m] = rsqrtf(fmaxf(s2 * (1.0f / 1024.0f) - mm * mm, 0.f) + LN_EPS_); }
;     __device__ __forceinline__ void operator()(const f32x4 (&acc)[2][2][4][2], const pg8::Unit& u, int wr, int wc, int fr, int fq) const {
;     ...
;         for (int ai = 0; ai < 2; ++ai) { float mu4[4], rs4[4]; row_stats4(stp, row0 + ai * 128, fq, mu4, rs4);
; #pragma unroll
;             for (int m = 0; m < 4; ++m) { const int row = row0 + ai * 128 + m * 16; const float mu = mu4[m], rs = rs4[m];
;                 f32x4 yv[2][2], gq[2][2], bq_[2][2];
; #pragma unroll
;                 for (int bj = 0; bj < 2; ++bj)
; #pragma unroll
;                     for (int n = 0; n < 2; ++n) { yv[bj][n] = *(const f32x4*)(Yin + (size_t)row * D_ + col0 + bj * 128 + 4 * n); gq[bj][n] = *(const f32x4*)(g + col0 + bj * 128 + 4 * n); bq_[bj][n] = *(const f32x4*)(b + col0 + bj * 128 + 4 * n); }
;                 asm volatile("" ::: "memory");
.LBB0_372:
	s_lshl_b32 s3, s3, 8
	s_add_i32 s3, s3, s53
	v_or_b32_e32 v158, s3, v182
	v_ashrrev_i32_e32 v159, 31, v158
	v_lshlrev_b64 v[130:131], 7, v[158:159]
	v_lshl_add_u64 v[136:137], v[146:147], 0, v[130:131]
	v_or_b32_e32 v180, 16, v158
	global_load_dwordx4 v[132:135], v[136:137], off
	global_load_dwordx4 v[166:169], v[136:137], off offset:16
	v_ashrrev_i32_e32 v181, 31, v180
	v_lshlrev_b64 v[172:173], 7, v[180:181]
	v_lshl_add_u64 v[136:137], v[146:147], 0, v[172:173]
	global_load_dwordx4 v[174:177], v[136:137], off
	global_load_dwordx4 v[186:189], v[136:137], off offset:16
	v_or_b32_e32 v170, 32, v158
	v_ashrrev_i32_e32 v171, 31, v170
	v_lshlrev_b64 v[164:165], 7, v[170:171]
	v_lshl_add_u64 v[136:137], v[146:147], 0, v[164:165]
	global_load_dwordx4 v[190:193], v[136:137], off
	global_load_dwordx4 v[196:199], v[136:137], off offset:16
	v_or_b32_e32 v162, 48, v158
	v_ashrrev_i32_e32 v163, 31, v162
	v_lshlrev_b64 v[160:161], 7, v[162:163]
	v_lshl_add_u64 v[204:205], v[146:147], 0, v[160:161]
	global_load_dwordx4 v[200:203], v[204:205], off
	s_nop 0
	global_load_dwordx4 v[204:207], v[204:205], off offset:16
	s_lshl_b32 s16, s2, 8
	s_lshl_b32 s17, s2, 3
	s_or_b32 s2, s16, s54
	v_or_b32_e32 v152, s2, v183
	v_ashrrev_i32_e32 v153, 31, v152
	v_lshlrev_b64 v[136:137], 12, v[158:159]
	v_lshlrev_b64 v[152:153], 2, v[152:153]
	v_lshl_add_u64 v[178:179], s[12:13], 0, v[136:137]
	v_lshl_add_u64 v[178:179], v[178:179], 0, v[152:153]
	v_lshl_add_u64 v[154:155], s[8:9], 0, v[152:153]
	v_lshl_add_u64 v[156:157], s[10:11], 0, v[152:153]
	global_load_dwordx4 v[208:211], v[178:179], off offset:16
	global_load_dwordx4 v[212:215], v[178:179], off
	global_load_dwordx4 v[216:219], v[154:155], off offset:16
	global_load_dwordx4 v[220:223], v[154:155], off
	global_load_dwordx4 v[234:237], v[156:157], off offset:16
	global_load_dwordx4 v[238:241], v[156:157], off
	s_mov_b32 s98, 0x10000
	s_mov_b32 s99, 0
	v_lshl_add_u64 v[224:225], v[178:179], 0, s[98:99]
	global_load_dword v0, v[224:225], off
	global_load_dword v0, v[224:225], off offset:512
	v_lshl_add_u64 v[224:225], v[224:225], 0, s[98:99]
	global_load_dword v0, v[224:225], off
	global_load_dword v0, v[224:225], off offset:512
	v_lshl_add_u64 v[224:225], v[224:225], 0, s[98:99]
	global_load_dword v0, v[224:225], off
	global_load_dword v0, v[224:225], off offset:512
	s_mov_b32 s98, 0x50000
	v_lshl_add_u64 v[224:225], v[224:225], 0, s[98:99]
	s_mov_b32 s98, 0x10000
	global_load_dword v0, v[224:225], off
	global_load_dword v0, v[224:225], off offset:512
	v_lshl_add_u64 v[224:225], v[224:225], 0, s[98:99]
	global_load_dword v0, v[224:225], off
	global_load_dword v0, v[224:225], off offset:512
	v_lshl_add_u64 v[224:225], v[224:225], 0, s[98:99]
	global_load_dword v0, v[224:225], off
	global_load_dword v0, v[224:225], off offset:512
	v_lshl_add_u64 v[224:225], v[224:225], 0, s[98:99]
	global_load_dword v0, v[224:225], off
	global_load_dword v0, v[224:225], off offset:512
	s_mov_b32 s16, 0x3a800000
	s_mov_b32 s18, 0x3fd744fd
	s_load_dwordx16 s[60:75], s[34:35], 0x38
	s_or_b32 s24, s17, s57
	v_bitop3_b32 v194, s2, 56, v183 bitop3:0xc8
	s_ashr_i32 s40, s2, 6
	s_ashr_i32 s25, s24, 31
	s_waitcnt lgkmcnt(0)
	v_lshl_add_u64 v[136:137], s[74:75], 0, v[136:137]
	v_lshl_add_u64 v[136:137], v[136:137], 0, v[152:153]
	s_ashr_i32 s41, s40, 31
	s_waitcnt vmcnt(0)
	v_mov_b32_e32 v224, v132
	v_mov_b32_e32 v225, v166
	v_mov_b32_e32 v228, v134
	v_mov_b32_e32 v229, v168
	v_mov_b32_e32 v166, v133
	v_mov_b32_e32 v168, v135
	v_pk_add_f32 v[132:133], v[224:225], v[228:229]
	v_pk_add_f32 v[134:135], v[166:167], v[168:169]
	v_pk_add_f32 v[132:133], v[132:133], v[132:133] op_sel:[0,1] op_sel_hi:[1,0]
	v_pk_add_f32 v[134:135], v[134:135], v[134:135] op_sel:[0,1] op_sel_hi:[1,0]
	v_mov_b32_e32 v166, v174
	v_mov_b32_e32 v167, v186
	v_mov_b32_e32 v168, v176
	v_mov_b32_e32 v169, v188
	v_mov_b32_e32 v0, v132
	v_mov_b32_e32 v133, v134
	v_pk_add_f32 v[166:167], v[166:167], v[168:169]
	v_permlane16_swap_b32_e32 v132, v0
	v_permlane16_swap_b32_e32 v134, v133
	v_mov_b32_e32 v186, v175
	v_mov_b32_e32 v188, v177
	v_pk_add_f32 v[166:167], v[166:167], v[166:167] op_sel:[0,1] op_sel_hi:[1,0]
	v_add_f32_e32 v177, v132, v0
	v_add_f32_e32 v176, v134, v133
	v_pk_add_f32 v[168:169], v[186:187], v[188:189]
	v_mov_b32_e32 v135, v166
	v_mov_b32_e32 v187, v177
	v_mov_b32_e32 v186, v176
	v_permlane16_swap_b32_e32 v166, v135
	v_permlane32_swap_b32_e32 v177, v187
	v_permlane32_swap_b32_e32 v176, v186
	v_add_f32_e32 v133, v166, v135
	v_pk_add_f32 v[166:167], v[176:177], v[186:187]
	v_pk_add_f32 v[168:169], v[168:169], v[168:169] op_sel:[0,1] op_sel_hi:[1,0]
	v_pk_mul_f32 v[224:225], v[166:167], s[16:17] op_sel_hi:[1,0]
	v_mov_b32_e32 v159, v168
	v_fma_f32 v0, -v225, v225, v224
	v_max_f32_e32 v0, 0, v0
	v_permlane16_swap_b32_e32 v168, v159
	v_add_f32_e32 v0, 0x3727c5ac, v0
	s_mov_b32 s16, 0x800000
	v_add_f32_e32 v132, v168, v159
	v_mul_f32_e32 v159, 0x4b800000, v0
	v_cmp_gt_f32_e32 vcc, s16, v0
	v_mov_b32_e32 v174, v190
	v_mov_b32_e32 v175, v196
	v_cndmask_b32_e32 v0, v0, v159, vcc
	v_rsq_f32_e32 v0, v0
	v_mov_b32_e32 v166, v192
	v_mov_b32_e32 v167, v198
	v_pk_add_f32 v[166:167], v[174:175], v[166:167]
	v_mul_f32_e32 v159, 0x45800000, v0
	v_pk_add_f32 v[166:167], v[166:167], v[166:167] op_sel:[0,1] op_sel_hi:[1,0]
	v_mov_b32_e32 v196, v191
	v_mov_b32_e32 v198, v193
	v_cndmask_b32_e32 v0, v0, v159, vcc
	v_pk_add_f32 v[168:169], v[196:197], v[198:199]
	v_mov_b32_e32 v159, v166
	v_pk_add_f32 v[168:169], v[168:169], v[168:169] op_sel:[0,1] op_sel_hi:[1,0]
	s_nop 0
	v_permlane16_swap_b32_e32 v166, v159
	v_add_f32_e32 v175, v166, v159
	v_mov_b32_e32 v159, v168
	s_nop 1
; __device__ __forceinline__ float xsum16(float v) { const auto r = __builtin_amdgcn_permlane16_swap(__float_as_uint(v), __float_as_uint(v), false, false); return __uint_as_float(r[0]) + __uint_as_float(r[1]); }
; __device__ __forceinline__ float xsum32(float v) { const auto r = __builtin_amdgcn_permlane32_swap(__float_as_uint(v), __float_as_uint(v), false, false); return __uint_as_float(r[0]) + __uint_as_float(r[1]); }
; __device__ __forceinline__ size_t blk_off(int r, int c, int K) { return (size_t)(r >> 8) * 256 * K + (size_t)(c >> 6) * (256 * 64) + (size_t)((r & 255) * 64 + (c & 63)); }
; __device__ __forceinline__ u32x4 pack8(const f32x4 a, const f32x4 b) { u32x4 w; w.x = cvt_pk_bf16(a[0], a[1]); w.y = cvt_pk_bf16(a[2], a[3]); w.z = cvt_pk_bf16(b[0], b[1]); w.w = cvt_pk_bf16(b[2], b[3]); return w; }
;     __device__ __forceinline__ void operator()(const f32x4 (&acc)[2][2][4][2], const pg8::Unit& u, int wr, int wc, int fr, int fq) const {
;     ...
;                 float s1 = 0.f, s2 = 0.f;
; #pragma unroll
;                 for (int bj = 0; bj < 2; ++bj) { float* yp = Y + (size_t)row * D_ + col0 + bj * 128; f32x4 v[2];
; #pragma unroll
;                     for (int n = 0; n < 2; ++n) { v[n] = (((yv[bj][n] - mu) * rs) * gq[bj][n] + bq_[bj][n]) * ALPHA_ + acc[ai][bj][m][n] * sc;
;                         *(f32x4*)(yp + 4 * n) = v[n]; s1 += (v[n][0] + v[n][1]) + (v[n][2] + v[n][3]); s2 += (v[n][0] * v[n][0] + v[n][1] * v[n][1]) + (v[n][2] * v[n][2] + v[n][3] * v[n][3]); }
;                     *(u32x4*)(Yb + blk_off(row, col0 + bj * 128, D_)) = pack8(v[0], v[1]); }
;                 s1 = xsum32(xsum16(s1)); s2 = xsum32(xsum16(s2));
;                 if (fq == 0) *(f32x2*)(stn + (size_t)row * 32 + (u.pn * 4 + wc) * 2) = (f32x2){s1, s2}; asm volatile("" ::: "memory"); } }
	v_permlane16_swap_b32_e32 v168, v159
	global_load_dwordx4 v[186:189], v[178:179], off offset:528
	global_load_dwordx4 v[190:193], v[178:179], off offset:512
	v_add_f32_e32 v174, v168, v159
	v_mov_b32_e32 v166, v200
	v_mov_b32_e32 v167, v204
	v_mov_b32_e32 v168, v202
	v_mov_b32_e32 v169, v206
	v_mov_b32_e32 v204, v201
	v_mov_b32_e32 v206, v203
	v_pk_add_f32 v[166:167], v[166:167], v[168:169]
	v_pk_add_f32 v[168:169], v[204:205], v[206:207]
	global_load_dwordx4 v[196:199], v[154:155], off offset:528
	global_load_dwordx4 v[200:203], v[154:155], off offset:512
	global_load_dwordx4 v[204:207], v[156:157], off offset:528
	global_load_dwordx4 v[242:245], v[156:157], off offset:512
	v_sub_f32_e32 v179, v215, v225
	v_sub_f32_e32 v178, v214, v225
	v_sub_f32_e32 v213, v213, v225
	v_sub_f32_e32 v212, v212, v225
	v_pk_mul_f32 v[212:213], v[0:1], v[212:213] op_sel_hi:[0,1]
	v_pk_mul_f32 v[178:179], v[0:1], v[178:179] op_sel_hi:[0,1]
	v_pk_fma_f32 v[178:179], v[222:223], v[178:179], v[240:241]
	v_pk_fma_f32 v[212:213], v[220:221], v[212:213], v[238:239]
	v_pk_mul_f32 v[178:179], v[178:179], s[18:19] op_sel_hi:[1,0]
	v_pk_mul_f32 v[212:213], v[212:213], s[18:19] op_sel_hi:[1,0]
	v_pk_fma_f32 v[128:129], v[128:129], 0.5, v[178:179] op_sel_hi:[1,0,1]
	v_pk_fma_f32 v[126:127], v[126:127], 0.5, v[212:213] op_sel_hi:[1,0,1]
	v_add_f32_e32 v179, v128, v129
	v_add_f32_e32 v178, v126, v127
	v_add_f32_e32 v178, v178, v179
	v_add_f32_e32 v195, 0, v178
	v_mul_f32_e32 v178, v127, v127
	v_mul_f32_e32 v179, v129, v129
	v_fmac_f32_e32 v178, v126, v126
	v_fmac_f32_e32 v179, v128, v128
	v_add_f32_e32 v212, v178, v179
	v_sub_f32_e32 v179, v211, v225
	v_sub_f32_e32 v178, v210, v225
	v_sub_f32_e32 v209, v209, v225
	v_sub_f32_e32 v208, v208, v225
	v_pk_mul_f32 v[208:209], v[0:1], v[208:209] op_sel_hi:[0,1]
	v_pk_mul_f32 v[178:179], v[0:1], v[178:179] op_sel_hi:[0,1]
	v_pk_fma_f32 v[178:179], v[218:219], v[178:179], v[236:237]
	v_pk_fma_f32 v[208:209], v[216:217], v[208:209], v[234:235]
	v_pk_mul_f32 v[178:179], v[178:179], s[18:19] op_sel_hi:[1,0]
	v_pk_mul_f32 v[208:209], v[208:209], s[18:19] op_sel_hi:[1,0]
	v_pk_add_f32 v[166:167], v[166:167], v[166:167] op_sel:[0,1] op_sel_hi:[1,0]
	v_pk_fma_f32 v[124:125], v[124:125], 0.5, v[178:179] op_sel_hi:[1,0,1]
	v_pk_fma_f32 v[122:123], v[122:123], 0.5, v[208:209] op_sel_hi:[1,0,1]
	v_mov_b32_e32 v159, v166
	v_add_f32_e32 v178, v122, v123
	v_add_f32_e32 v179, v124, v125
	v_pk_add_f32 v[168:169], v[168:169], v[168:169] op_sel:[0,1] op_sel_hi:[1,0]
	v_permlane16_swap_b32_e32 v166, v159
	v_add_f32_e32 v178, v178, v179
	v_add_f32_e32 v167, v166, v159
	v_mov_b32_e32 v159, v168
	v_add_f32_e32 v178, v195, v178
	v_mul_f32_e32 v179, v123, v123
	v_mul_f32_e32 v195, v125, v125
	v_permlane16_swap_b32_e32 v168, v159
	s_ashr_i32 s16, s3, 8
	global_store_dwordx4 v[136:137], v[126:129], off
	global_store_dwordx4 v[136:137], v[122:125], off offset:16
	v_fmac_f32_e32 v179, v122, v122
	v_fmac_f32_e32 v195, v124, v124
	v_cvt_pk_bf16_f32 v126, v126, v127
	v_cvt_pk_bf16_f32 v127, v128, v129
	v_cvt_pk_bf16_f32 v128, v122, v123
	v_cvt_pk_bf16_f32 v129, v124, v125
	v_add_f32_e32 v166, v168, v159
	s_ashr_i32 s17, s16, 31
	v_lshlrev_b32_e32 v159, 6, v158
	s_movk_i32 s3, 0x33c0
	s_lshl_b64 s[16:17], s[16:17], 19
	v_and_or_b32 v159, v159, s3, v194
	v_readlane_b32 s2, v253, 59
	v_readlane_b32 s3, v253, 60
	s_add_u32 s16, s2, s16
	s_addc_u32 s17, s3, s17
	s_lshl_b64 s[28:29], s[40:41], 15
	s_waitcnt vmcnt(6)
	v_sub_f32_e32 v123, v193, v225
	v_sub_f32_e32 v122, v192, v225
	v_sub_f32_e32 v125, v191, v225
	v_sub_f32_e32 v124, v190, v225
	v_pk_mul_f32 v[124:125], v[0:1], v[124:125] op_sel_hi:[0,1]
	v_pk_mul_f32 v[122:123], v[0:1], v[122:123] op_sel_hi:[0,1]
	s_add_u32 s50, s16, s28
	s_addc_u32 s51, s17, s29
	v_lshlrev_b32_e32 v159, 1, v159
	global_store_dwordx4 v159, v[126:129], s[50:51]
	s_waitcnt vmcnt(3)
	v_pk_fma_f32 v[122:123], v[202:203], v[122:123], v[244:245]
	v_pk_fma_f32 v[124:125], v[200:201], v[124:125], v[242:243]
	v_pk_mul_f32 v[122:123], v[122:123], s[18:19] op_sel_hi:[1,0]
	v_pk_mul_f32 v[124:125], v[124:125], s[18:19] op_sel_hi:[1,0]
	v_pk_fma_f32 v[120:121], v[120:121], 0.5, v[122:123] op_sel_hi:[1,0,1]
	v_pk_fma_f32 v[118:119], v[118:119], 0.5, v[124:125] op_sel_hi:[1,0,1]
	v_add_f32_e32 v123, v120, v121
	v_add_f32_e32 v122, v118, v119
	v_add_f32_e32 v122, v122, v123
	v_add_f32_e32 v126, v178, v122
	v_mul_f32_e32 v122, v119, v119
	v_mul_f32_e32 v123, v121, v121
	v_add_f32_e32 v179, v179, v195
	v_fmac_f32_e32 v122, v118, v118
	v_fmac_f32_e32 v123, v120, v120
	v_add_f32_e32 v179, v212, v179
	v_add_f32_e32 v122, v122, v123
	v_add_f32_e32 v127, v179, v122
	v_sub_f32_e32 v123, v189, v225
	v_sub_f32_e32 v122, v188, v225
	v_sub_f32_e32 v125, v187, v225
	v_sub_f32_e32 v124, v186, v225
	v_pk_mul_f32 v[124:125], v[0:1], v[124:125] op_sel_hi:[0,1]
	v_pk_mul_f32 v[122:123], v[0:1], v[122:123] op_sel_hi:[0,1]
	v_pk_fma_f32 v[122:123], v[198:199], v[122:123], v[206:207]
	v_pk_fma_f32 v[124:125], v[196:197], v[124:125], v[204:205]
	v_pk_mul_f32 v[122:123], v[122:123], s[18:19] op_sel_hi:[1,0]
	v_pk_mul_f32 v[124:125], v[124:125], s[18:19] op_sel_hi:[1,0]
	v_pk_fma_f32 v[116:117], v[116:117], 0.5, v[122:123] op_sel_hi:[1,0,1]
	v_pk_fma_f32 v[114:115], v[114:115], 0.5, v[124:125] op_sel_hi:[1,0,1]
	v_add_f32_e32 v122, v116, v117
	v_add_f32_e32 v0, v114, v115
	v_add_f32_e32 v0, v0, v122
	v_mul_f32_e32 v122, v115, v115
	v_mul_f32_e32 v123, v117, v117
	v_add_f32_e32 v0, v126, v0
	v_fmac_f32_e32 v122, v114, v114
	v_fmac_f32_e32 v123, v116, v116
	global_store_dwordx4 v[136:137], v[118:121], off offset:512
	global_store_dwordx4 v[136:137], v[114:117], off offset:528
	v_add_f32_e32 v122, v122, v123
	v_cvt_pk_bf16_f32 v118, v118, v119
	v_cvt_pk_bf16_f32 v119, v120, v121
	v_cvt_pk_bf16_f32 v120, v114, v115
	v_mov_b32_e32 v114, v0
	v_add_f32_e32 v122, v127, v122
	s_nop 0
	v_permlane16_swap_b32_e32 v0, v114
	s_or_b32 s2, s40, 2
	v_add_f32_e32 v114, v0, v114
	v_mov_b32_e32 v0, v122
	s_ashr_i32 s3, s2, 31
	s_nop 0
	v_permlane16_swap_b32_e32 v122, v0
	s_lshl_b64 s[40:41], s[2:3], 15
	v_add_f32_e32 v115, v122, v0
	v_mov_b32_e32 v135, v133
	v_mov_b32_e32 v134, v132
	v_mov_b32_e32 v177, v175
	v_mov_b32_e32 v176, v174
	v_mov_b32_e32 v169, v167
	v_mov_b32_e32 v168, v166
	v_cvt_pk_bf16_f32 v121, v116, v117
	s_add_u32 s42, s16, s40
	v_mov_b32_e32 v116, v114
	v_mov_b32_e32 v117, v115
	v_permlane32_swap_b32_e32 v133, v135
	v_permlane32_swap_b32_e32 v132, v134
	v_permlane32_swap_b32_e32 v175, v177
	v_permlane32_swap_b32_e32 v174, v176
	v_permlane32_swap_b32_e32 v167, v169
	v_permlane32_swap_b32_e32 v166, v168
	s_addc_u32 s43, s17, s41
	v_permlane32_swap_b32_e32 v114, v116
	v_permlane32_swap_b32_e32 v115, v117
	global_store_dwordx4 v159, v[118:121], s[42:43]
	s_and_saveexec_b64 s[26:27], s[44:45]
	s_cbranch_execz .LBB0_374
	v_pk_add_f32 v[114:115], v[114:115], v[116:117]
	v_lshl_add_u64 v[116:117], s[30:31], 0, v[130:131]
	v_lshl_add_u64 v[116:117], s[24:25], 2, v[116:117]
	global_store_dwordx2 v[116:117], v[114:115], off

; #define LAS __attribute__((address_space(3)))
; #define MFMA16(a, b, c) __builtin_amdgcn_mfma_f32_16x16x32_bf16((a), (b), (c), 0, 0, 0)
; template <class MaskF>
; __device__ __forceinline__ void attn_step(const KVRegs& r, const bf16x8 (&bq)[2], LAS unsigned char* vl, int lane, const MaskF mask, float& m, float& l, f32x4 (&o)[4]) {
;     ...
;     { LAS unsigned char* wp = vl + (lane >> 1) * 128 + (lane & 1) * 64;
; #pragma unroll
;       for (int i = 0; i < 4; ++i) *(LAS u32x4*)(wp + 16 * i) = r.v[i]; }
;     f32x4 sa = (f32x4){0.f, 0.f, 0.f, 0.f}, sb = (f32x4){0.f, 0.f, 0.f, 0.f};
;     sa = MFMA16(r.ka[0], bq[0], sa); sa = MFMA16(r.ka[1], bq[1], sa);
;     sb = MFMA16(r.kb[0], bq[0], sb); sb = MFMA16(r.kb[1], bq[1], sb);
; __device__ __forceinline__ void kv_gather(KVRegs& r, const bf16_t* Pb, const LAS unsigned short* il, int s, int lane) {
;     const int li = lane & 15, g4 = lane >> 4;
;     const unsigned ra = il[32 * s + li], rb = il[32 * s + 16 + li], rv = il[32 * s + (lane >> 1)];
;     const bf16_t* k0 = Pb + (size_t)ra * NP_ + PC_KC + 8 * g4; const bf16_t* k1 = Pb + (size_t)rb * NP_ + PC_KC + 8 * g4;
;     r.ka[0] = *(const bf16x8*)k0; r.ka[1] = *(const bf16x8*)(k0 + 32); r.kb[0] = *(const bf16x8*)k1; r.kb[1] = *(const bf16x8*)(k1 + 32);
;     const bf16_t* vp = Pb + (size_t)rv * NP_ + PC_VC + (lane & 1) * 32;
; #pragma unroll
;     for (int i = 0; i < 4; ++i) r.v[i] = *(const u32x4*)(vp + 8 * i);
; }
.LBB0_1169:
	s_cmp_lt_i32 s7, s8
	s_cbranch_scc0 .LBB0_1171
	v_add_u32_e32 v0, s9, v109
	v_add_u32_e32 v2, 0x10140, v0
	v_add_u32_e32 v0, 0x10160, v0
	ds_read_u16 v2, v2
	ds_read_u16 v3, v0
	v_add_u32_e32 v0, s9, v108
	v_add_u32_e32 v0, 0x10140, v0
	ds_read_u16 v20, v0
	s_waitcnt lgkmcnt(2)
	v_mul_u32_u24_e32 v0, 0x1c00, v2
	s_waitcnt lgkmcnt(1)
	v_mul_u32_u24_e32 v2, 0x1c00, v3
	v_mov_b32_e32 v3, v1
	v_lshl_add_u64 v[4:5], s[4:5], 0, v[0:1]
	v_mov_b32_e32 v95, v1
	v_lshl_add_u64 v[2:3], s[4:5], 0, v[2:3]
	v_lshl_add_u64 v[4:5], v[4:5], 0, v[94:95]
	s_mov_b64 s[0:1], 0x1500
	v_lshl_add_u64 v[2:3], v[2:3], 0, v[94:95]
	v_lshl_add_u64 v[12:13], v[4:5], 0, s[0:1]
	v_lshl_add_u64 v[16:17], v[2:3], 0, s[0:1]
	s_movk_i32 s0, 0x1000
	v_add_co_u32_e32 v4, vcc, s0, v4
	v_mov_b32_e32 v93, v1
	s_nop 0
	v_addc_co_u32_e32 v5, vcc, 0, v5, vcc
	v_add_co_u32_e32 v2, vcc, s0, v2
	s_mov_b64 s[0:1], 0x1b00
	s_nop 0
	v_addc_co_u32_e32 v3, vcc, 0, v3, vcc
	global_load_dwordx4 v[4:7], v[4:5], off offset:1280
	s_nop 0
	global_load_dwordx4 v[8:11], v[2:3], off offset:1280
	s_nop 0
	global_load_dwordx4 v[12:15], v[12:13], off offset:64
	s_nop 0
	global_load_dwordx4 v[16:19], v[16:17], off offset:64
	v_mov_b64_e32 v[2:3], s[4:5]
	s_waitcnt lgkmcnt(0)
	v_mad_u64_u32 v[2:3], s[10:11], v20, s21, v[2:3]
	v_lshl_add_u64 v[2:3], v[2:3], 0, v[92:93]
	v_lshl_add_u64 v[32:33], v[2:3], 0, s[0:1]
	v_add_co_u32_e32 v2, vcc, 0x1000, v2
	s_nop 1
	v_addc_co_u32_e32 v3, vcc, 0, v3, vcc
	global_load_dwordx4 v[20:23], v[2:3], off offset:2816
	global_load_dwordx4 v[24:27], v[32:33], off offset:48
	global_load_dwordx4 v[28:31], v[32:33], off offset:32
	s_nop 0
	global_load_dwordx4 v[32:35], v[32:33], off offset:16
	s_waitcnt vmcnt(10)
	v_mfma_f32_16x16x32_bf16 v[112:115], v[76:79], v[68:71], 0
	v_subrev_u32_e32 v0, 32, v99
	v_cmp_lt_i32_e32 vcc, v0, v101
	v_add_u32_e32 v0, -16, v99
	v_mfma_f32_16x16x32_bf16 v[118:121], v[64:67], v[68:71], 0
	v_add_u32_e32 v3, v104, v105
	s_waitcnt vmcnt(9)
	ds_write_b128 v3, v[84:87]
	s_waitcnt vmcnt(8)
	ds_write_b128 v3, v[56:59] offset:16
	ds_write_b128 v3, v[52:55] offset:32
	s_waitcnt vmcnt(8)
	ds_write_b128 v3, v[88:91] offset:48
	s_branch .Ldsa3_tailA_0

; #define LAS __attribute__((address_space(3)))
; __device__ __forceinline__ float fast_exp2(float x) { return __builtin_amdgcn_exp2f(x); }
; template <class MaskF>
; __device__ __forceinline__ void attn_step(const KVRegs& r, const bf16x8 (&bq)[2], LAS unsigned char* vl, int lane, const MaskF mask, float& m, float& l, f32x4 (&o)[4]) {
;     ...
;     float x[8];
; #pragma unroll
;     for (int e = 0; e < 4; ++e) { x[e] = mask(4 * g4 + e, sa[e]); x[4 + e] = mask(16 + 4 * g4 + e, sb[e]); }
;     float tm = fmaxf(fmaxf(fmaxf(x[0], x[1]), fmaxf(x[2], x[3])), fmaxf(fmaxf(x[4], x[5]), fmaxf(x[6], x[7])));
;     tm = xmax32(xmax16(tm));
;     const float mn = fmaxf(m, tm);
;     if (__ballot(mn > m)) { const float al = fast_exp2(m - mn); l *= al;
; #pragma unroll
;         for (int db = 0; db < 4; ++db) o[db] = o[db] * al; }
;     m = mn;
;     float p[8], ps = 0.f;
; #pragma unroll
;     for (int e = 0; e < 8; ++e) { p[e] = fast_exp2(x[e] - mn); ps += p[e]; }
;     l += ps;
;     u32x4 pw; pw.x = cvt_pk_bf16(p[0], p[1]); pw.y = cvt_pk_bf16(p[2], p[3]); pw.z = cvt_pk_bf16(p[4], p[5]); pw.w = cvt_pk_bf16(p[6], p[7]);
;     const bf16x8 pf = __builtin_bit_cast(bf16x8, pw);
;     asm volatile("s_waitcnt lgkmcnt(0)" ::: "memory");
;     LAS unsigned char* rd = vl + (4 * g4 + ((lane & 15) >> 2)) * 128 + (lane & 3) * 8;
; #pragma unroll
;     for (int db = 0; db < 4; ++db) { const s16x4 t0 = tr_read(rd + db * 32), t1 = tr_read(rd + 16 * 128 + db * 32);
;         const bf16x8 vf = (bf16x8){t0[0], t0[1], t0[2], t0[3], t1[0], t1[1], t1[2], t1[3]};
;         o[db] = MFMA16(vf, pf, o[db]); }
;     asm volatile("s_waitcnt lgkmcnt(0)" ::: "memory");
; }
; __device__ __forceinline__ void kv_gather(KVRegs& r, const bf16_t* Pb, const LAS unsigned short* il, int s, int lane) {
;     const int li = lane & 15, g4 = lane >> 4;
;     const unsigned ra = il[32 * s + li], rb = il[32 * s + 16 + li], rv = il[32 * s + (lane >> 1)];
;     const bf16_t* k0 = Pb + (size_t)ra * NP_ + PC_KC + 8 * g4; const bf16_t* k1 = Pb + (size_t)rb * NP_ + PC_KC + 8 * g4;
;     r.ka[0] = *(const bf16x8*)k0; r.ka[1] = *(const bf16x8*)(k0 + 32); r.kb[0] = *(const bf16x8*)k1; r.kb[1] = *(const bf16x8*)(k1 + 32);
;     const bf16_t* vp = Pb + (size_t)rv * NP_ + PC_VC + (lane & 1) * 32;
; #pragma unroll
;     for (int i = 0; i < 4; ++i) r.v[i] = *(const u32x4*)(vp + 8 * i);
; }
.Ldsa3_tailA_0:
	v_mfma_f32_16x16x32_bf16 v[114:117], v[80:83], v[72:75], v[112:115]
	v_mfma_f32_16x16x32_bf16 v[118:121], v[60:63], v[72:75], v[118:121]
	s_nop 6
	v_cndmask_b32_e32 v112, v233, v114, vcc
	v_cmp_lt_i32_e32 vcc, v0, v101
	v_subrev_u32_e32 v0, 31, v99
	s_nop 0
	v_cndmask_b32_e32 v95, v233, v118, vcc
	v_cmp_lt_i32_e32 vcc, v0, v101
	v_add_u32_e32 v0, -15, v99
	s_nop 0
	v_cndmask_b32_e32 v114, v233, v115, vcc
	v_cmp_lt_i32_e32 vcc, v0, v101
	v_subrev_u32_e32 v0, 30, v99
	v_max_f32_e32 v103, v114, v114
	v_cndmask_b32_e32 v93, v233, v119, vcc
	v_cmp_lt_i32_e32 vcc, v0, v101
	v_add_u32_e32 v0, -14, v99
	v_max_f32_e32 v115, v112, v112
	v_cndmask_b32_e32 v113, v233, v116, vcc
	v_cmp_lt_i32_e32 vcc, v0, v101
	v_subrev_u32_e32 v0, 29, v99
	v_max_f32_e32 v103, v115, v103
	v_cndmask_b32_e32 v2, v233, v120, vcc
	v_cmp_lt_i32_e32 vcc, v0, v101
	v_add_u32_e32 v0, -13, v99
	v_max_f32_e32 v116, v113, v113
	v_cndmask_b32_e32 v111, v233, v117, vcc
	v_cmp_lt_i32_e32 vcc, v0, v101
	v_max_f32_e32 v115, v111, v111
	v_max_f32_e32 v115, v116, v115
	v_cndmask_b32_e32 v0, v233, v121, vcc
	v_max_f32_e32 v116, v0, v0
	v_max_f32_e32 v117, v2, v2
	v_max_f32_e32 v116, v117, v116
	v_max3_f32 v116, v95, v93, v116
	v_max3_f32 v103, v103, v115, v116
	v_mov_b32_e32 v115, v103
	s_nop 1
	v_permlane16_swap_b32_e32 v103, v115
	v_max_f32_e32 v115, v115, v115
	v_max_f32_e32 v103, v103, v103
	v_max_f32_e32 v103, v103, v115
	v_mov_b32_e32 v115, v103
	s_nop 1
	v_permlane32_swap_b32_e32 v103, v115
	v_max3_f32 v103, v102, v103, v115
	v_cmp_gt_f32_e32 vcc, v103, v102
	s_cbranch_vccz .LBB0_1173
	v_sub_f32_e32 v102, v102, v103
	v_exp_f32_e32 v102, v102
	s_nop 0
	v_mul_f32_e32 v97, v97, v102
	v_pk_mul_f32 v[50:51], v[50:51], v[102:103] op_sel_hi:[1,0]
	v_pk_mul_f32 v[48:49], v[48:49], v[102:103] op_sel_hi:[1,0]
	v_pk_mul_f32 v[46:47], v[46:47], v[102:103] op_sel_hi:[1,0]
	v_pk_mul_f32 v[44:45], v[44:45], v[102:103] op_sel_hi:[1,0]
	v_pk_mul_f32 v[42:43], v[42:43], v[102:103] op_sel_hi:[1,0]
	v_pk_mul_f32 v[40:41], v[40:41], v[102:103] op_sel_hi:[1,0]
	v_pk_mul_f32 v[38:39], v[38:39], v[102:103] op_sel_hi:[1,0]
	v_pk_mul_f32 v[36:37], v[36:37], v[102:103] op_sel_hi:[1,0]
.LBB0_1173:
	v_sub_f32_e32 v102, v112, v103
	v_exp_f32_e32 v102, v102
	v_sub_f32_e32 v114, v114, v103
	v_exp_f32_e32 v114, v114
	v_sub_f32_e32 v113, v113, v103
	v_exp_f32_e32 v113, v113
	v_sub_f32_e32 v111, v111, v103
	v_exp_f32_e32 v111, v111
	v_sub_f32_e32 v95, v95, v103
	v_add_f32_e32 v112, 0, v102
	v_exp_f32_e32 v95, v95
	v_sub_f32_e32 v93, v93, v103
	v_add_f32_e32 v112, v114, v112
	v_exp_f32_e32 v93, v93
	v_sub_f32_e32 v2, v2, v103
	v_sub_f32_e32 v0, v0, v103
	v_add_f32_e32 v112, v113, v112
	v_exp_f32_e32 v2, v2
	v_exp_f32_e32 v0, v0
	v_add_f32_e32 v112, v111, v112
	v_add_f32_e32 v112, v95, v112
	v_add_f32_e32 v112, v93, v112
	v_add_f32_e32 v112, v2, v112
	v_cvt_pk_bf16_f32 v115, v2, v0
	s_waitcnt lgkmcnt(0)
	v_add_u32_e32 v2, v106, v107
	ds_read_b64_tr_b16 v[118:119], v2 offset:2048
	ds_read_b64_tr_b16 v[116:117], v2
	ds_read_b64_tr_b16 v[120:121], v2 offset:32
	v_add_f32_e32 v112, v0, v112
	v_add_f32_e32 v97, v112, v97
	v_cvt_pk_bf16_f32 v112, v102, v114
	v_cvt_pk_bf16_f32 v113, v113, v111
	v_cvt_pk_bf16_f32 v114, v95, v93
	ds_read_b64_tr_b16 v[122:123], v2 offset:2080
	s_add_i32 s0, s7, 1
	s_waitcnt lgkmcnt(2)
	v_mfma_f32_16x16x32_bf16 v[48:51], v[116:119], v[112:115], v[48:51]
	ds_read_b64_tr_b16 v[116:117], v2 offset:64
	ds_read_b64_tr_b16 v[118:119], v2 offset:2112
	s_cmp_ge_i32 s0, s6
	s_waitcnt lgkmcnt(0)
	v_mfma_f32_16x16x32_bf16 v[40:43], v[116:119], v[112:115], v[40:43]
	ds_read_b64_tr_b16 v[116:117], v2 offset:96
	ds_read_b64_tr_b16 v[118:119], v2 offset:2144
	s_waitcnt lgkmcnt(0)
	v_mfma_f32_16x16x32_bf16 v[44:47], v[120:123], v[112:115], v[44:47]
	s_waitcnt lgkmcnt(0)
	v_mfma_f32_16x16x32_bf16 v[36:39], v[116:119], v[112:115], v[36:39]
	s_cbranch_scc1 .LBB0_1167
	s_cmp_ge_i32 s0, s8
	s_cbranch_scc1 .LBB0_1176
	v_add_u32_e32 v0, s9, v109
	v_add_u32_e32 v52, 0x10180, v0
	v_add_u32_e32 v0, 0x101a0, v0
	ds_read_u16 v52, v52
	ds_read_u16 v53, v0
	v_add_u32_e32 v0, s9, v108
	v_add_u32_e32 v0, 0x10180, v0
	ds_read_u16 v84, v0
	s_waitcnt lgkmcnt(2)
	v_mul_u32_u24_e32 v0, 0x1c00, v52
	s_waitcnt lgkmcnt(1)
	v_mul_u32_u24_e32 v52, 0x1c00, v53
	v_mov_b32_e32 v53, v1
	v_lshl_add_u64 v[54:55], s[4:5], 0, v[0:1]
	v_mov_b32_e32 v95, v1
	v_lshl_add_u64 v[52:53], s[4:5], 0, v[52:53]
	v_lshl_add_u64 v[54:55], v[54:55], 0, v[94:95]
	s_mov_b64 s[0:1], 0x1500
	v_lshl_add_u64 v[52:53], v[52:53], 0, v[94:95]
	v_lshl_add_u64 v[56:57], v[54:55], 0, s[0:1]
	v_lshl_add_u64 v[58:59], v[52:53], 0, s[0:1]
	s_movk_i32 s0, 0x1000
	v_add_co_u32_e32 v54, vcc, s0, v54
	v_mov_b32_e32 v93, v1
	s_nop 0
	v_addc_co_u32_e32 v55, vcc, 0, v55, vcc
	v_add_co_u32_e32 v52, vcc, s0, v52
	s_nop 1
	v_addc_co_u32_e32 v53, vcc, 0, v53, vcc
	global_load_dwordx4 v[76:79], v[54:55], off offset:1280
	global_load_dwordx4 v[64:67], v[52:53], off offset:1280
	global_load_dwordx4 v[80:83], v[56:57], off offset:64
	global_load_dwordx4 v[60:63], v[58:59], off offset:64
	v_mov_b64_e32 v[52:53], s[4:5]
	s_waitcnt lgkmcnt(0)
	v_mad_u64_u32 v[52:53], s[10:11], v84, s21, v[52:53]
	v_lshl_add_u64 v[52:53], v[52:53], 0, v[92:93]
	s_mov_b64 s[10:11], 0x1b00
	v_lshl_add_u64 v[56:57], v[52:53], 0, s[10:11]
	v_add_co_u32_e32 v52, vcc, s0, v52
	s_nop 1
	v_addc_co_u32_e32 v53, vcc, 0, v53, vcc
	global_load_dwordx4 v[84:87], v[52:53], off offset:2816
	global_load_dwordx4 v[88:91], v[56:57], off offset:48
	s_nop 0
	global_load_dwordx4 v[52:55], v[56:57], off offset:32
	s_nop 0
	global_load_dwordx4 v[56:59], v[56:57], off offset:16
	s_waitcnt vmcnt(8)
	s_branch .Ldsa3_bodyB_0
; #define LAS __attribute__((address_space(3)))
; __device__ __forceinline__ float fast_exp2(float x) { return __builtin_amdgcn_exp2f(x); }
; __device__ __forceinline__ float xmax16(float v) { const auto r = __builtin_amdgcn_permlane16_swap(__float_as_uint(v), __float_as_uint(v), false, false); return fmaxf(__uint_as_float(r[0]), __uint_as_float(r[1])); }
; __device__ __forceinline__ float xmax32(float v) { const auto r = __builtin_amdgcn_permlane32_swap(__float_as_uint(v), __float_as_uint(v), false, false); return fmaxf(__uint_as_float(r[0]), __uint_as_float(r[1])); }
; #define MFMA16(a, b, c) __builtin_amdgcn_mfma_f32_16x16x32_bf16((a), (b), (c), 0, 0, 0)
; template <class MaskF>
; __device__ __forceinline__ void attn_step(const KVRegs& r, const bf16x8 (&bq)[2], LAS unsigned char* vl, int lane, const MaskF mask, float& m, float& l, f32x4 (&o)[4]) {
;     ...
;     { LAS unsigned char* wp = vl + (lane >> 1) * 128 + (lane & 1) * 64;
; #pragma unroll
;       for (int i = 0; i < 4; ++i) *(LAS u32x4*)(wp + 16 * i) = r.v[i]; }
;     f32x4 sa = (f32x4){0.f, 0.f, 0.f, 0.f}, sb = (f32x4){0.f, 0.f, 0.f, 0.f};
;     sa = MFMA16(r.ka[0], bq[0], sa); sa = MFMA16(r.ka[1], bq[1], sa);
;     sb = MFMA16(r.kb[0], bq[0], sb); sb = MFMA16(r.kb[1], bq[1], sb);
;     float x[8];
; #pragma unroll
;     for (int e = 0; e < 4; ++e) { x[e] = mask(4 * g4 + e, sa[e]); x[4 + e] = mask(16 + 4 * g4 + e, sb[e]); }
;     float tm = fmaxf(fmaxf(fmaxf(x[0], x[1]), fmaxf(x[2], x[3])), fmaxf(fmaxf(x[4], x[5]), fmaxf(x[6], x[7])));
;     tm = xmax32(xmax16(tm));
;     const float mn = fmaxf(m, tm);
;     if (__ballot(mn > m)) { const float al = fast_exp2(m - mn); l *= al;
; #pragma unroll
;         for (int db = 0; db < 4; ++db) o[db] = o[db] * al; }
.LBB0_1176:
	s_waitcnt vmcnt(0)
.Ldsa3_bodyB_0:
	v_mfma_f32_16x16x32_bf16 v[112:115], v[4:7], v[68:71], 0
	v_cmp_lt_i32_e32 vcc, v99, v101
	v_add_u32_e32 v0, 16, v99
	ds_write_b128 v3, v[20:23]
	v_mfma_f32_16x16x32_bf16 v[118:121], v[8:11], v[68:71], 0
	ds_write_b128 v3, v[32:35] offset:16
	ds_write_b128 v3, v[28:31] offset:32
	ds_write_b128 v3, v[24:27] offset:48
	v_mfma_f32_16x16x32_bf16 v[114:117], v[12:15], v[72:75], v[112:115]
	v_mfma_f32_16x16x32_bf16 v[118:121], v[16:19], v[72:75], v[118:121]
	s_nop 6
	v_cndmask_b32_e32 v112, v233, v114, vcc
	v_cmp_lt_i32_e32 vcc, v0, v101
	v_add_u32_e32 v0, 1, v99
	s_nop 0
	v_cndmask_b32_e32 v95, v233, v118, vcc
	v_cmp_lt_i32_e32 vcc, v0, v101
	v_add_u32_e32 v0, 17, v99
	s_nop 0
	v_cndmask_b32_e32 v114, v233, v115, vcc
	v_cmp_lt_i32_e32 vcc, v0, v101
	v_add_u32_e32 v0, 2, v99
	v_max_f32_e32 v102, v114, v114
	v_cndmask_b32_e32 v93, v233, v119, vcc
	v_cmp_lt_i32_e32 vcc, v0, v101
	v_add_u32_e32 v0, 18, v99
	v_max_f32_e32 v115, v112, v112
	v_cndmask_b32_e32 v113, v233, v116, vcc
	v_cmp_lt_i32_e32 vcc, v0, v101
	v_add_u32_e32 v0, 3, v99
	v_max_f32_e32 v102, v115, v102
	v_cndmask_b32_e32 v3, v233, v120, vcc
	v_cmp_lt_i32_e32 vcc, v0, v101
	v_add_u32_e32 v0, 19, v99
	v_max_f32_e32 v116, v113, v113
	v_cndmask_b32_e32 v111, v233, v117, vcc
	v_cmp_lt_i32_e32 vcc, v0, v101
	v_max_f32_e32 v115, v111, v111
	v_max_f32_e32 v115, v116, v115
	v_cndmask_b32_e32 v0, v233, v121, vcc
	v_max_f32_e32 v116, v0, v0
	v_max_f32_e32 v117, v3, v3
	v_max_f32_e32 v116, v117, v116
	v_max3_f32 v116, v95, v93, v116
	v_max3_f32 v102, v102, v115, v116
	v_mov_b32_e32 v115, v102
	s_nop 1
	v_permlane16_swap_b32_e32 v102, v115
	v_max_f32_e32 v115, v115, v115
	v_max_f32_e32 v102, v102, v102
	v_max_f32_e32 v102, v102, v115
	v_mov_b32_e32 v115, v102
	s_nop 1
	v_permlane32_swap_b32_e32 v102, v115
	v_max3_f32 v102, v103, v102, v115
	v_cmp_gt_f32_e32 vcc, v102, v103
	s_cbranch_vccz .LBB0_1178
	v_sub_f32_e32 v103, v103, v102
	v_exp_f32_e32 v116, v103
	s_nop 0
	v_mul_f32_e32 v97, v97, v116
	v_pk_mul_f32 v[50:51], v[50:51], v[116:117] op_sel_hi:[1,0]
	v_pk_mul_f32 v[48:49], v[48:49], v[116:117] op_sel_hi:[1,0]
	v_pk_mul_f32 v[46:47], v[46:47], v[116:117] op_sel_hi:[1,0]
	v_pk_mul_f32 v[44:45], v[44:45], v[116:117] op_sel_hi:[1,0]
	v_pk_mul_f32 v[42:43], v[42:43], v[116:117] op_sel_hi:[1,0]
	v_pk_mul_f32 v[40:41], v[40:41], v[116:117] op_sel_hi:[1,0]
	v_pk_mul_f32 v[38:39], v[38:39], v[116:117] op_sel_hi:[1,0]
	v_pk_mul_f32 v[36:37], v[36:37], v[116:117] op_sel_hi:[1,0]

; #define LAS __attribute__((address_space(3)))
; #define MFMA16(a, b, c) __builtin_amdgcn_mfma_f32_16x16x32_bf16((a), (b), (c), 0, 0, 0)
; template <class MaskF>
; __device__ __forceinline__ void attn_step(const KVRegs& r, const bf16x8 (&bq)[2], LAS unsigned char* vl, int lane, const MaskF mask, float& m, float& l, f32x4 (&o)[4]) {
;     ...
;     { LAS unsigned char* wp = vl + (lane >> 1) * 128 + (lane & 1) * 64;
; #pragma unroll
;       for (int i = 0; i < 4; ++i) *(LAS u32x4*)(wp + 16 * i) = r.v[i]; }
;     f32x4 sa = (f32x4){0.f, 0.f, 0.f, 0.f}, sb = (f32x4){0.f, 0.f, 0.f, 0.f};
;     sa = MFMA16(r.ka[0], bq[0], sa); sa = MFMA16(r.ka[1], bq[1], sa);
;     sb = MFMA16(r.kb[0], bq[0], sb); sb = MFMA16(r.kb[1], bq[1], sb);
; __device__ __forceinline__ void kv_gather(KVRegs& r, const bf16_t* Pb, const LAS unsigned short* il, int s, int lane) {
;     const int li = lane & 15, g4 = lane >> 4;
;     const unsigned ra = il[32 * s + li], rb = il[32 * s + 16 + li], rv = il[32 * s + (lane >> 1)];
;     const bf16_t* k0 = Pb + (size_t)ra * NP_ + PC_KC + 8 * g4; const bf16_t* k1 = Pb + (size_t)rb * NP_ + PC_KC + 8 * g4;
;     r.ka[0] = *(const bf16x8*)k0; r.ka[1] = *(const bf16x8*)(k0 + 32); r.kb[0] = *(const bf16x8*)k1; r.kb[1] = *(const bf16x8*)(k1 + 32);
;     const bf16_t* vp = Pb + (size_t)rv * NP_ + PC_VC + (lane & 1) * 32;
; #pragma unroll
;     for (int i = 0; i < 4; ++i) r.v[i] = *(const u32x4*)(vp + 8 * i);
; }
.LBB0_1186:
	s_cmp_ge_i32 s8, s7
	s_cbranch_scc1 .LBB0_1188
	v_add_u32_e32 v0, s9, v109
	v_add_u32_e32 v2, 0x10340, v0
	v_add_u32_e32 v0, 0x10360, v0
	ds_read_u16 v2, v2
	ds_read_u16 v3, v0
	v_add_u32_e32 v0, s9, v108
	v_add_u32_e32 v0, 0x10340, v0
	ds_read_u16 v20, v0
	s_waitcnt lgkmcnt(2)
	v_mul_u32_u24_e32 v0, 0x1c00, v2
	s_waitcnt lgkmcnt(1)
	v_mul_u32_u24_e32 v2, 0x1c00, v3
	v_mov_b32_e32 v3, v1
	v_lshl_add_u64 v[4:5], s[4:5], 0, v[0:1]
	v_mov_b32_e32 v95, v1
	v_lshl_add_u64 v[2:3], s[4:5], 0, v[2:3]
	v_lshl_add_u64 v[4:5], v[4:5], 0, v[94:95]
	s_mov_b64 s[0:1], 0x1500
	v_lshl_add_u64 v[2:3], v[2:3], 0, v[94:95]
	v_lshl_add_u64 v[12:13], v[4:5], 0, s[0:1]
	v_lshl_add_u64 v[16:17], v[2:3], 0, s[0:1]
	s_movk_i32 s0, 0x1000
	v_add_co_u32_e32 v4, vcc, s0, v4
	v_mov_b32_e32 v93, v1
	s_nop 0
	v_addc_co_u32_e32 v5, vcc, 0, v5, vcc
	v_add_co_u32_e32 v2, vcc, s0, v2
	s_mov_b64 s[0:1], 0x1b00
	s_nop 0
	v_addc_co_u32_e32 v3, vcc, 0, v3, vcc
	global_load_dwordx4 v[4:7], v[4:5], off offset:1280
	s_nop 0
	global_load_dwordx4 v[8:11], v[2:3], off offset:1280
	s_nop 0
	global_load_dwordx4 v[12:15], v[12:13], off offset:64
	s_nop 0
	global_load_dwordx4 v[16:19], v[16:17], off offset:64
	v_mov_b64_e32 v[2:3], s[4:5]
	s_waitcnt lgkmcnt(0)
	v_mad_u64_u32 v[2:3], s[10:11], v20, s21, v[2:3]
	v_lshl_add_u64 v[2:3], v[2:3], 0, v[92:93]
	v_lshl_add_u64 v[32:33], v[2:3], 0, s[0:1]
	v_add_co_u32_e32 v2, vcc, 0x1000, v2
	s_nop 1
	v_addc_co_u32_e32 v3, vcc, 0, v3, vcc
	global_load_dwordx4 v[20:23], v[2:3], off offset:2816
	global_load_dwordx4 v[24:27], v[32:33], off offset:48
	global_load_dwordx4 v[28:31], v[32:33], off offset:32
	s_nop 0
	global_load_dwordx4 v[32:35], v[32:33], off offset:16
	s_waitcnt vmcnt(10)
	v_mfma_f32_16x16x32_bf16 v[112:115], v[76:79], v[68:71], 0
	v_subrev_u32_e32 v0, 32, v110
	v_cmp_lt_i32_e32 vcc, v0, v101
	v_add_u32_e32 v0, -16, v110
	v_mfma_f32_16x16x32_bf16 v[116:119], v[60:63], v[68:71], 0
	v_add_u32_e32 v3, v104, v105
	s_waitcnt vmcnt(9)
	ds_write_b128 v3, v[84:87]
	s_waitcnt vmcnt(8)
	ds_write_b128 v3, v[48:51] offset:16
	ds_write_b128 v3, v[44:47] offset:32
	s_waitcnt vmcnt(8)
	ds_write_b128 v3, v[88:91] offset:48
	s_branch .Ldsa3_tailA_1

; #define LAS __attribute__((address_space(3)))
; __device__ __forceinline__ float fast_exp2(float x) { return __builtin_amdgcn_exp2f(x); }
; template <class MaskF>
; __device__ __forceinline__ void attn_step(const KVRegs& r, const bf16x8 (&bq)[2], LAS unsigned char* vl, int lane, const MaskF mask, float& m, float& l, f32x4 (&o)[4]) {
;     ...
;     float x[8];
; #pragma unroll
;     for (int e = 0; e < 4; ++e) { x[e] = mask(4 * g4 + e, sa[e]); x[4 + e] = mask(16 + 4 * g4 + e, sb[e]); }
;     float tm = fmaxf(fmaxf(fmaxf(x[0], x[1]), fmaxf(x[2], x[3])), fmaxf(fmaxf(x[4], x[5]), fmaxf(x[6], x[7])));
;     tm = xmax32(xmax16(tm));
;     const float mn = fmaxf(m, tm);
;     if (__ballot(mn > m)) { const float al = fast_exp2(m - mn); l *= al;
; #pragma unroll
;         for (int db = 0; db < 4; ++db) o[db] = o[db] * al; }
;     m = mn;
;     float p[8], ps = 0.f;
; #pragma unroll
;     for (int e = 0; e < 8; ++e) { p[e] = fast_exp2(x[e] - mn); ps += p[e]; }
;     l += ps;
;     u32x4 pw; pw.x = cvt_pk_bf16(p[0], p[1]); pw.y = cvt_pk_bf16(p[2], p[3]); pw.z = cvt_pk_bf16(p[4], p[5]); pw.w = cvt_pk_bf16(p[6], p[7]);
;     const bf16x8 pf = __builtin_bit_cast(bf16x8, pw);
;     asm volatile("s_waitcnt lgkmcnt(0)" ::: "memory");
;     LAS unsigned char* rd = vl + (4 * g4 + ((lane & 15) >> 2)) * 128 + (lane & 3) * 8;
; #pragma unroll
;     for (int db = 0; db < 4; ++db) { const s16x4 t0 = tr_read(rd + db * 32), t1 = tr_read(rd + 16 * 128 + db * 32);
;         const bf16x8 vf = (bf16x8){t0[0], t0[1], t0[2], t0[3], t1[0], t1[1], t1[2], t1[3]};
;         o[db] = MFMA16(vf, pf, o[db]); }
;     asm volatile("s_waitcnt lgkmcnt(0)" ::: "memory");
; }
; __device__ __forceinline__ void kv_gather(KVRegs& r, const bf16_t* Pb, const LAS unsigned short* il, int s, int lane) {
;     const int li = lane & 15, g4 = lane >> 4;
;     const unsigned ra = il[32 * s + li], rb = il[32 * s + 16 + li], rv = il[32 * s + (lane >> 1)];
;     const bf16_t* k0 = Pb + (size_t)ra * NP_ + PC_KC + 8 * g4; const bf16_t* k1 = Pb + (size_t)rb * NP_ + PC_KC + 8 * g4;
;     r.ka[0] = *(const bf16x8*)k0; r.ka[1] = *(const bf16x8*)(k0 + 32); r.kb[0] = *(const bf16x8*)k1; r.kb[1] = *(const bf16x8*)(k1 + 32);
;     const bf16_t* vp = Pb + (size_t)rv * NP_ + PC_VC + (lane & 1) * 32;
; #pragma unroll
;     for (int i = 0; i < 4; ++i) r.v[i] = *(const u32x4*)(vp + 8 * i);
; }
.Ldsa3_tailA_1:
	v_mfma_f32_16x16x32_bf16 v[112:115], v[80:83], v[72:75], v[112:115]
	v_mfma_f32_16x16x32_bf16 v[116:119], v[56:59], v[72:75], v[116:119]
	s_nop 6
	v_cndmask_b32_e32 v103, v233, v112, vcc
	v_cmp_lt_i32_e32 vcc, v0, v101
	v_subrev_u32_e32 v0, 31, v110
	s_nop 0
	v_cndmask_b32_e32 v95, v233, v116, vcc
	v_cmp_lt_i32_e32 vcc, v0, v101
	v_add_u32_e32 v0, -15, v110
	s_nop 0
	v_cndmask_b32_e32 v112, v233, v113, vcc
	v_cmp_lt_i32_e32 vcc, v0, v101
	v_subrev_u32_e32 v0, 30, v110
	v_max_f32_e32 v98, v112, v112
	v_cndmask_b32_e32 v93, v233, v117, vcc
	v_cmp_lt_i32_e32 vcc, v0, v101
	v_add_u32_e32 v0, -14, v110
	v_max_f32_e32 v113, v103, v103
	v_cndmask_b32_e32 v111, v233, v114, vcc
	v_cmp_lt_i32_e32 vcc, v0, v101
	v_subrev_u32_e32 v0, 29, v110
	v_max_f32_e32 v98, v113, v98
	v_cndmask_b32_e32 v2, v233, v118, vcc
	v_cmp_lt_i32_e32 vcc, v0, v101
	v_add_u32_e32 v0, -13, v110
	v_max_f32_e32 v114, v111, v111
	v_cndmask_b32_e32 v99, v233, v115, vcc
	v_cmp_lt_i32_e32 vcc, v0, v101
	v_max_f32_e32 v113, v99, v99
	v_max_f32_e32 v113, v114, v113
	v_cndmask_b32_e32 v0, v233, v119, vcc
	v_max_f32_e32 v114, v0, v0
	v_max_f32_e32 v115, v2, v2
	v_max_f32_e32 v114, v115, v114
	v_max3_f32 v114, v95, v93, v114
	v_max3_f32 v98, v98, v113, v114
	v_mov_b32_e32 v113, v98
	s_nop 1
	v_permlane16_swap_b32_e32 v98, v113
	v_max_f32_e32 v113, v113, v113
	v_max_f32_e32 v98, v98, v98
	v_max_f32_e32 v98, v98, v113
	v_mov_b32_e32 v113, v98
	s_nop 1
	v_permlane32_swap_b32_e32 v98, v113
	v_max3_f32 v98, v97, v98, v113
	v_cmp_gt_f32_e32 vcc, v98, v97
	s_cbranch_vccz .LBB0_1190
	v_sub_f32_e32 v97, v97, v98
	v_exp_f32_e32 v114, v97
	s_nop 0
	v_mul_f32_e32 v96, v96, v114
	v_pk_mul_f32 v[66:67], v[66:67], v[114:115] op_sel_hi:[1,0]
	v_pk_mul_f32 v[64:65], v[64:65], v[114:115] op_sel_hi:[1,0]
	v_pk_mul_f32 v[54:55], v[54:55], v[114:115] op_sel_hi:[1,0]
	v_pk_mul_f32 v[52:53], v[52:53], v[114:115] op_sel_hi:[1,0]
	v_pk_mul_f32 v[42:43], v[42:43], v[114:115] op_sel_hi:[1,0]
	v_pk_mul_f32 v[40:41], v[40:41], v[114:115] op_sel_hi:[1,0]
	v_pk_mul_f32 v[38:39], v[38:39], v[114:115] op_sel_hi:[1,0]
	v_pk_mul_f32 v[36:37], v[36:37], v[114:115] op_sel_hi:[1,0]
.LBB0_1190:
	v_sub_f32_e32 v97, v103, v98
	v_exp_f32_e32 v97, v97
	v_sub_f32_e32 v112, v112, v98
	v_exp_f32_e32 v112, v112
	v_sub_f32_e32 v111, v111, v98
	v_exp_f32_e32 v111, v111
	v_sub_f32_e32 v99, v99, v98
	v_exp_f32_e32 v99, v99
	v_sub_f32_e32 v95, v95, v98
	v_add_f32_e32 v103, 0, v97
	v_exp_f32_e32 v95, v95
	v_sub_f32_e32 v93, v93, v98
	v_add_f32_e32 v103, v112, v103
	v_exp_f32_e32 v93, v93
	v_sub_f32_e32 v2, v2, v98
	v_sub_f32_e32 v0, v0, v98
	v_add_f32_e32 v103, v111, v103
	v_exp_f32_e32 v2, v2
	v_exp_f32_e32 v0, v0
	v_add_f32_e32 v103, v99, v103
	v_add_f32_e32 v103, v95, v103
	v_add_f32_e32 v103, v93, v103
	v_add_f32_e32 v103, v2, v103
	v_cvt_pk_bf16_f32 v115, v2, v0
	s_waitcnt lgkmcnt(0)
	v_add_u32_e32 v2, v106, v107
	ds_read_b64_tr_b16 v[118:119], v2 offset:2048
	ds_read_b64_tr_b16 v[116:117], v2
	ds_read_b64_tr_b16 v[120:121], v2 offset:32
	v_cvt_pk_bf16_f32 v112, v97, v112
	v_cvt_pk_bf16_f32 v113, v111, v99
	v_cvt_pk_bf16_f32 v114, v95, v93
	ds_read_b64_tr_b16 v[122:123], v2 offset:2080
	v_add_f32_e32 v103, v0, v103
	s_waitcnt lgkmcnt(2)
	v_mfma_f32_16x16x32_bf16 v[64:67], v[116:119], v[112:115], v[64:67]
	ds_read_b64_tr_b16 v[116:117], v2 offset:64
	ds_read_b64_tr_b16 v[118:119], v2 offset:2112
	s_add_i32 s0, s8, 1
	v_add_f32_e32 v96, v103, v96
	s_waitcnt lgkmcnt(0)
	v_mfma_f32_16x16x32_bf16 v[40:43], v[116:119], v[112:115], v[40:43]
	ds_read_b64_tr_b16 v[116:117], v2 offset:96
	ds_read_b64_tr_b16 v[118:119], v2 offset:2144
	s_waitcnt lgkmcnt(0)
	s_cmp_ge_i32 s0, s6
	v_mfma_f32_16x16x32_bf16 v[52:55], v[120:123], v[112:115], v[52:55]
	s_waitcnt lgkmcnt(0)
	v_mfma_f32_16x16x32_bf16 v[36:39], v[116:119], v[112:115], v[36:39]
	s_cbranch_scc1 .LBB0_1184
	s_cmp_ge_i32 s0, s7
	s_cbranch_scc1 .LBB0_1193
	v_add_u32_e32 v0, s9, v109
	v_add_u32_e32 v44, 0x10380, v0
	v_add_u32_e32 v0, 0x103a0, v0
	ds_read_u16 v44, v44
	ds_read_u16 v45, v0
	v_add_u32_e32 v0, s9, v108
	v_add_u32_e32 v0, 0x10380, v0
	ds_read_u16 v84, v0
	s_waitcnt lgkmcnt(2)
	v_mul_u32_u24_e32 v0, 0x1c00, v44
	s_waitcnt lgkmcnt(1)
	v_mul_u32_u24_e32 v44, 0x1c00, v45
	v_mov_b32_e32 v45, v1
	v_lshl_add_u64 v[46:47], s[4:5], 0, v[0:1]
	v_mov_b32_e32 v95, v1
	v_lshl_add_u64 v[44:45], s[4:5], 0, v[44:45]
	v_lshl_add_u64 v[46:47], v[46:47], 0, v[94:95]
	s_mov_b64 s[0:1], 0x1500
	v_lshl_add_u64 v[44:45], v[44:45], 0, v[94:95]
	v_lshl_add_u64 v[48:49], v[46:47], 0, s[0:1]
	v_lshl_add_u64 v[50:51], v[44:45], 0, s[0:1]
	s_movk_i32 s0, 0x1000
	v_add_co_u32_e32 v46, vcc, s0, v46
	v_mov_b32_e32 v93, v1
	s_nop 0
	v_addc_co_u32_e32 v47, vcc, 0, v47, vcc
	v_add_co_u32_e32 v44, vcc, s0, v44
	s_nop 1
	v_addc_co_u32_e32 v45, vcc, 0, v45, vcc
	global_load_dwordx4 v[76:79], v[46:47], off offset:1280
	global_load_dwordx4 v[60:63], v[44:45], off offset:1280
	global_load_dwordx4 v[80:83], v[48:49], off offset:64
	global_load_dwordx4 v[56:59], v[50:51], off offset:64
	v_mov_b64_e32 v[44:45], s[4:5]
	s_waitcnt lgkmcnt(0)
	v_mad_u64_u32 v[44:45], s[10:11], v84, s21, v[44:45]
	v_lshl_add_u64 v[44:45], v[44:45], 0, v[92:93]
	s_mov_b64 s[10:11], 0x1b00
	v_lshl_add_u64 v[48:49], v[44:45], 0, s[10:11]
	v_add_co_u32_e32 v44, vcc, s0, v44
	s_nop 1
	v_addc_co_u32_e32 v45, vcc, 0, v45, vcc
	global_load_dwordx4 v[84:87], v[44:45], off offset:2816
	global_load_dwordx4 v[88:91], v[48:49], off offset:48
	s_nop 0
	global_load_dwordx4 v[44:47], v[48:49], off offset:32
	s_nop 0
	global_load_dwordx4 v[48:51], v[48:49], off offset:16
	s_waitcnt vmcnt(8)
	s_branch .Ldsa3_bodyB_1
; #define LAS __attribute__((address_space(3)))
; __device__ __forceinline__ float fast_exp2(float x) { return __builtin_amdgcn_exp2f(x); }
; __device__ __forceinline__ float xmax16(float v) { const auto r = __builtin_amdgcn_permlane16_swap(__float_as_uint(v), __float_as_uint(v), false, false); return fmaxf(__uint_as_float(r[0]), __uint_as_float(r[1])); }
; __device__ __forceinline__ float xmax32(float v) { const auto r = __builtin_amdgcn_permlane32_swap(__float_as_uint(v), __float_as_uint(v), false, false); return fmaxf(__uint_as_float(r[0]), __uint_as_float(r[1])); }
; #define MFMA16(a, b, c) __builtin_amdgcn_mfma_f32_16x16x32_bf16((a), (b), (c), 0, 0, 0)
; template <class MaskF>
; __device__ __forceinline__ void attn_step(const KVRegs& r, const bf16x8 (&bq)[2], LAS unsigned char* vl, int lane, const MaskF mask, float& m, float& l, f32x4 (&o)[4]) {
;     ...
;     { LAS unsigned char* wp = vl + (lane >> 1) * 128 + (lane & 1) * 64;
; #pragma unroll
;       for (int i = 0; i < 4; ++i) *(LAS u32x4*)(wp + 16 * i) = r.v[i]; }
;     f32x4 sa = (f32x4){0.f, 0.f, 0.f, 0.f}, sb = (f32x4){0.f, 0.f, 0.f, 0.f};
;     sa = MFMA16(r.ka[0], bq[0], sa); sa = MFMA16(r.ka[1], bq[1], sa);
;     sb = MFMA16(r.kb[0], bq[0], sb); sb = MFMA16(r.kb[1], bq[1], sb);
;     float x[8];
; #pragma unroll
;     for (int e = 0; e < 4; ++e) { x[e] = mask(4 * g4 + e, sa[e]); x[4 + e] = mask(16 + 4 * g4 + e, sb[e]); }
;     float tm = fmaxf(fmaxf(fmaxf(x[0], x[1]), fmaxf(x[2], x[3])), fmaxf(fmaxf(x[4], x[5]), fmaxf(x[6], x[7])));
;     tm = xmax32(xmax16(tm));
;     const float mn = fmaxf(m, tm);
;     if (__ballot(mn > m)) { const float al = fast_exp2(m - mn); l *= al;
; #pragma unroll
;         for (int db = 0; db < 4; ++db) o[db] = o[db] * al; }
.LBB0_1193:
	s_waitcnt vmcnt(0)
.Ldsa3_bodyB_1:
	v_mfma_f32_16x16x32_bf16 v[112:115], v[4:7], v[68:71], 0
	v_cmp_lt_i32_e32 vcc, v110, v101
	v_add_u32_e32 v0, 16, v110
	ds_write_b128 v3, v[20:23]
	v_mfma_f32_16x16x32_bf16 v[116:119], v[8:11], v[68:71], 0
	ds_write_b128 v3, v[32:35] offset:16
	ds_write_b128 v3, v[28:31] offset:32
	ds_write_b128 v3, v[24:27] offset:48
	v_mfma_f32_16x16x32_bf16 v[112:115], v[12:15], v[72:75], v[112:115]
	v_mfma_f32_16x16x32_bf16 v[116:119], v[16:19], v[72:75], v[116:119]
	s_nop 6
	v_cndmask_b32_e32 v103, v233, v112, vcc
	v_cmp_lt_i32_e32 vcc, v0, v101
	v_add_u32_e32 v0, 1, v110
	s_nop 0
	v_cndmask_b32_e32 v95, v233, v116, vcc
	v_cmp_lt_i32_e32 vcc, v0, v101
	v_add_u32_e32 v0, 17, v110
	s_nop 0
	v_cndmask_b32_e32 v112, v233, v113, vcc
	v_cmp_lt_i32_e32 vcc, v0, v101
	v_add_u32_e32 v0, 2, v110
	v_max_f32_e32 v97, v112, v112
	v_cndmask_b32_e32 v93, v233, v117, vcc
	v_cmp_lt_i32_e32 vcc, v0, v101
	v_add_u32_e32 v0, 18, v110
	v_max_f32_e32 v113, v103, v103
	v_cndmask_b32_e32 v111, v233, v114, vcc
	v_cmp_lt_i32_e32 vcc, v0, v101
	v_add_u32_e32 v0, 3, v110
	v_max_f32_e32 v97, v113, v97
	v_cndmask_b32_e32 v3, v233, v118, vcc
	v_cmp_lt_i32_e32 vcc, v0, v101
	v_add_u32_e32 v0, 19, v110
	v_max_f32_e32 v114, v111, v111
	v_cndmask_b32_e32 v99, v233, v115, vcc
	v_cmp_lt_i32_e32 vcc, v0, v101
	v_max_f32_e32 v113, v99, v99
	v_max_f32_e32 v113, v114, v113
	v_cndmask_b32_e32 v0, v233, v119, vcc
	v_max_f32_e32 v114, v0, v0
	v_max_f32_e32 v115, v3, v3
	v_max_f32_e32 v114, v115, v114
	v_max3_f32 v114, v95, v93, v114
	v_max3_f32 v97, v97, v113, v114
	v_mov_b32_e32 v113, v97
	s_nop 1
	v_permlane16_swap_b32_e32 v97, v113
	v_max_f32_e32 v113, v113, v113
	v_max_f32_e32 v97, v97, v97
	v_max_f32_e32 v97, v97, v113
	v_mov_b32_e32 v113, v97
	s_nop 1
	v_permlane32_swap_b32_e32 v97, v113
	v_max3_f32 v97, v98, v97, v113
	v_cmp_gt_f32_e32 vcc, v97, v98
	s_cbranch_vccz .LBB0_1195
	v_sub_f32_e32 v98, v98, v97
	v_exp_f32_e32 v98, v98
	s_nop 0
	v_mul_f32_e32 v96, v96, v98
	v_pk_mul_f32 v[66:67], v[66:67], v[98:99] op_sel_hi:[1,0]
	v_pk_mul_f32 v[64:65], v[64:65], v[98:99] op_sel_hi:[1,0]
	v_pk_mul_f32 v[54:55], v[54:55], v[98:99] op_sel_hi:[1,0]
	v_pk_mul_f32 v[52:53], v[52:53], v[98:99] op_sel_hi:[1,0]
	v_pk_mul_f32 v[42:43], v[42:43], v[98:99] op_sel_hi:[1,0]
	v_pk_mul_f32 v[40:41], v[40:41], v[98:99] op_sel_hi:[1,0]
	v_pk_mul_f32 v[38:39], v[38:39], v[98:99] op_sel_hi:[1,0]
	v_pk_mul_f32 v[36:37], v[36:37], v[98:99] op_sel_hi:[1,0]

; __device__ __forceinline__ void kv_load(KVRegs& r, const bf16_t* kbase, size_t kst, const bf16_t* vbase, int s, int lane) {
;     const int li = lane & 15, g4 = lane >> 4;
;     const bf16_t* k0 = kbase + (size_t)(32 * s + li) * kst + 8 * g4;
;     r.ka[0] = *(const bf16x8*)k0; r.ka[1] = *(const bf16x8*)(k0 + 32);
;     const bf16_t* k1 = k0 + 16 * kst;
;     r.kb[0] = *(const bf16x8*)k1; r.kb[1] = *(const bf16x8*)(k1 + 32);
;     const bf16_t* vp = vbase + (size_t)(32 * s + (lane >> 1)) * kst + (lane & 1) * 32;
; #pragma unroll
;     for (int i = 0; i < 4; ++i) r.v[i] = *(const u32x4*)(vp + 8 * i);
; }
; template <int NQ>
; __device__ __forceinline__ void band_unit(int u, const bf16_t* P, bf16_t* OB, bf16_t* ACX, float* LSE, const float* sink, LAS unsigned char* vl, int lane_in) {
;     ...
;     for (int s = s_lo; s <= s_hi; s += RING) {
; #pragma unroll
;         for (int j = 0; j < RING; ++j) {
;             if (s + j <= s_hi) {
;                 if (s + j + RING - 1 <= s_hi) kv_load(kv[(j + RING - 1) % RING], kbase, kst, vbase, s + j + RING - 1, lane);
;                 band_step<NQ>(kv[j], bq, vl, lane, s + j, q0, W, m, l, o);
.LBB0_1211:
	v_lshl_add_u64 v[130:131], v[204:205], 0, s[28:29]
	v_add_co_u32_e32 v130, vcc, 0x8800000, v130
	s_nop 0
	v_lshl_add_u64 v[138:139], v[200:201], 0, s[28:29]
	v_addc_co_u32_e32 v131, vcc, 0, v131, vcc
	v_add_co_u32_e32 v138, vcc, 0x8800000, v138
	s_nop 0
	v_lshl_add_u64 v[158:159], v[202:203], 0, s[28:29]
	v_addc_co_u32_e32 v139, vcc, 0, v139, vcc
	global_load_dwordx4 v[134:137], v[130:131], off
	s_nop 0
	global_load_dwordx4 v[130:133], v[130:131], off offset:64
	s_nop 0
	global_load_dwordx4 v[150:153], v[138:139], off
	global_load_dwordx4 v[146:149], v[138:139], off offset:64
	s_nop 0
	global_load_dwordx4 v[138:141], v[158:159], off offset:16
	global_load_dwordx4 v[142:145], v[158:159], off
	global_load_dwordx4 v[154:157], v[158:159], off offset:-16
	s_nop 0
	global_load_dwordx4 v[158:161], v[158:159], off offset:-32
	s_waitcnt vmcnt(8)
	s_branch .Lband_bodyA

; #define LAS __attribute__((address_space(3)))
; template <int NQ>
; __device__ __forceinline__ void band_step(const KVRegs& r, const bf16x8 (&bq)[NQ][2], LAS unsigned char* vl, int lane, int s, int q0, int W, float (&m)[NQ], float (&l)[NQ], f32x4 (&o)[NQ][4]) {
;     ...
;     { LAS unsigned char* wp = vl + (lane >> 1) * 128 + (lane & 1) * 64;
; #pragma unroll
;       for (int i = 0; i < 4; ++i) *(LAS u32x4*)(wp + 16 * i) = r.v[i]; }
;     asm volatile("s_waitcnt lgkmcnt(0)" ::: "memory");
;     bf16x8 vf[4];
;     { LAS unsigned char* rd = vl + (4 * g4 + (qi >> 2)) * 128 + (lane & 3) * 8;
; #pragma unroll
;       for (int db = 0; db < 4; ++db) { const s16x4 t0 = tr_read(rd + db * 32), t1 = tr_read(rd + 16 * 128 + db * 32);
;           vf[db] = (bf16x8){t0[0], t0[1], t0[2], t0[3], t1[0], t1[1], t1[2], t1[3]}; } }
; #pragma unroll
;     for (int g = 0; g < NQ; ++g) {
;         const int qlo = q0 + 16 * g;
;         if (32 * s <= qlo + 15 && 32 * s + 31 >= qlo - W) {
;             f32x4 sa = (f32x4){0.f, 0.f, 0.f, 0.f}, sb = (f32x4){0.f, 0.f, 0.f, 0.f};
;             sa = MFMA16(r.ka[0], bq[g][0], sa); sa = MFMA16(r.ka[1], bq[g][1], sa);
;             sb = MFMA16(r.kb[0], bq[g][0], sb); sb = MFMA16(r.kb[1], bq[g][1], sb);
;             const BandMask mask{32 * s, qlo + qi, W};
;             float x[8];
; #pragma unroll
;             for (int e = 0; e < 4; ++e) { x[e] = mask(4 * g4 + e, sa[e]); x[4 + e] = mask(16 + 4 * g4 + e, sb[e]); }
;             float tm = fmaxf(fmaxf(fmaxf(x[0], x[1]), fmaxf(x[2], x[3])), fmaxf(fmaxf(x[4], x[5]), fmaxf(x[6], x[7])));
;             tm = xmax32(xmax16(tm));
;             const float mn = fmaxf(m[g], tm);
;             if (__ballot(mn > m[g])) { const float al = fast_exp2(m[g] - mn); l[g] *= al;
; #pragma unroll
;                 for (int db = 0; db < 4; ++db) o[g][db] = o[g][db] * al; }
;             m[g] = mn;
;             float pp[8], ps = 0.f;
; #pragma unroll
;             for (int e = 0; e < 8; ++e) { pp[e] = fast_exp2(x[e] - mn); ps += pp[e]; }
;             l[g] += ps;
;             u32x4 pw; pw.x = cvt_pk_bf16(pp[0], pp[1]); pw.y = cvt_pk_bf16(pp[2], pp[3]); pw.z = cvt_pk_bf16(pp[4], pp[5]); pw.w = cvt_pk_bf16(pp[6], pp[7]);
;             const bf16x8 pf = __builtin_bit_cast(bf16x8, pw);
; #pragma unroll
;             for (int db = 0; db < 4; ++db) o[g][db] = MFMA16(vf[db], pf, o[g][db]);
.Lband_bodyA:
	ds_write_b128 v0, v[110:113]
	ds_write_b128 v0, v[106:109] offset:16
	ds_write_b128 v0, v[102:105] offset:32
	ds_write_b128 v0, v[98:101] offset:48
	s_waitcnt lgkmcnt(0)
	s_waitcnt lgkmcnt(11)
	ds_read_b64_tr_b16 v[174:175], v216
	s_waitcnt lgkmcnt(11)
	ds_read_b64_tr_b16 v[170:171], v216 offset:32
	s_waitcnt lgkmcnt(9)
	ds_read_b64_tr_b16 v[176:177], v216 offset:2048
	s_waitcnt lgkmcnt(9)
	ds_read_b64_tr_b16 v[172:173], v216 offset:2080
	ds_read_b64_tr_b16 v[166:167], v216 offset:64
	s_waitcnt lgkmcnt(10)
	ds_read_b64_tr_b16 v[168:169], v216 offset:2112
	ds_read_b64_tr_b16 v[162:163], v216 offset:96
	s_waitcnt lgkmcnt(11)
	ds_read_b64_tr_b16 v[164:165], v216 offset:2144
	s_add_i32 s2, s42, 31
	s_cmp_gt_i32 s42, s43
	s_cselect_b64 s[4:5], -1, 0
	s_cmp_lt_i32 s2, s46
	s_cselect_b64 s[6:7], -1, 0
	s_or_b64 s[4:5], s[4:5], s[6:7]
	v_subrev_u32_e32 v230, 48, v222
	v_subrev_u32_e32 v228, 49, v222
	v_subrev_u32_e32 v224, 50, v222
	v_subrev_u32_e32 v223, 51, v222
	s_and_b64 vcc, exec, s[4:5]
	v_subrev_u32_e32 v217, 64, v222
	v_cmp_ge_u32_e64 s[10:11], s23, v230
	v_cmp_ge_u32_e64 s[8:9], s23, v228
	v_cmp_ge_u32_e64 s[6:7], s23, v224
	v_cmp_ge_u32_e64 s[4:5], s23, v223
	s_cbranch_vccnz .LBB0_1216
	s_waitcnt vmcnt(8)
	v_mfma_f32_16x16x32_bf16 v[186:189], v[118:121], v[50:53], 0
	v_subrev_u32_e32 v225, 64, v222
	v_cmp_ge_u32_e32 vcc, s23, v225
	v_mfma_f32_16x16x32_bf16 v[190:193], v[126:129], v[50:53], 0
	v_mfma_f32_16x16x32_bf16 v[186:189], v[114:117], v[54:57], v[186:189]
	v_mfma_f32_16x16x32_bf16 v[190:193], v[122:125], v[54:57], v[190:193]
	s_nop 6
	v_cndmask_b32_e64 v239, v233, v186, s[10:11]
	v_add_u32_e32 v186, 0xffffffbf, v222
	v_cndmask_b32_e32 v235, v233, v190, vcc
	v_cmp_ge_u32_e32 vcc, s23, v186
	v_add_u32_e32 v186, 0xffffffbe, v222
	v_cndmask_b32_e64 v238, v233, v187, s[8:9]
	v_cndmask_b32_e32 v234, v233, v191, vcc
	v_cmp_ge_u32_e32 vcc, s23, v186
	v_add_u32_e32 v186, 0xffffffbd, v222
	v_cndmask_b32_e64 v237, v233, v188, s[6:7]
	v_cndmask_b32_e32 v229, v233, v192, vcc
	v_cndmask_b32_e64 v236, v233, v189, s[4:5]
	v_cmp_ge_u32_e32 vcc, s23, v186
	v_max_f32_e32 v186, v238, v238
	v_max_f32_e32 v187, v239, v239
	v_cndmask_b32_e32 v226, v233, v193, vcc
	v_max_f32_e32 v186, v187, v186
	v_max_f32_e32 v187, v236, v236
	v_max_f32_e32 v188, v237, v237
	v_max_f32_e32 v187, v188, v187
	v_max_f32_e32 v188, v226, v226
	v_max_f32_e32 v189, v229, v229
	v_max_f32_e32 v188, v189, v188
	v_max3_f32 v188, v235, v234, v188
	v_max3_f32 v186, v186, v187, v188
	v_mov_b32_e32 v187, v186
	s_nop 1
	v_permlane16_swap_b32_e32 v186, v187
	v_max_f32_e32 v187, v187, v187
	v_max_f32_e32 v186, v186, v186
	v_max_f32_e32 v186, v186, v187
	v_mov_b32_e32 v187, v186
	s_nop 1
	v_permlane32_swap_b32_e32 v186, v187
	v_max3_f32 v225, v221, v186, v187
	v_cmp_gt_f32_e32 vcc, v225, v221
	s_cbranch_vccz .LBB0_1215
	v_sub_f32_e32 v186, v221, v225
	v_exp_f32_e32 v186, v186
	s_nop 0
	v_mul_f32_e32 v209, v209, v186
	v_pk_mul_f32 v[96:97], v[96:97], v[186:187] op_sel_hi:[1,0]
	v_pk_mul_f32 v[94:95], v[94:95], v[186:187] op_sel_hi:[1,0]
	v_pk_mul_f32 v[92:93], v[92:93], v[186:187] op_sel_hi:[1,0]
	v_pk_mul_f32 v[90:91], v[90:91], v[186:187] op_sel_hi:[1,0]
	v_pk_mul_f32 v[88:89], v[88:89], v[186:187] op_sel_hi:[1,0]
	v_pk_mul_f32 v[86:87], v[86:87], v[186:187] op_sel_hi:[1,0]
	v_pk_mul_f32 v[84:85], v[84:85], v[186:187] op_sel_hi:[1,0]
	v_pk_mul_f32 v[82:83], v[82:83], v[186:187] op_sel_hi:[1,0]

; __device__ __forceinline__ float fast_exp2(float x) { return __builtin_amdgcn_exp2f(x); }
; __device__ __forceinline__ float xmax16(float v) { const auto r = __builtin_amdgcn_permlane16_swap(__float_as_uint(v), __float_as_uint(v), false, false); return fmaxf(__uint_as_float(r[0]), __uint_as_float(r[1])); }
; __device__ __forceinline__ float xmax32(float v) { const auto r = __builtin_amdgcn_permlane32_swap(__float_as_uint(v), __float_as_uint(v), false, false); return fmaxf(__uint_as_float(r[0]), __uint_as_float(r[1])); }
; #define MFMA16(a, b, c) __builtin_amdgcn_mfma_f32_16x16x32_bf16((a), (b), (c), 0, 0, 0)
; template <int NQ>
; __device__ __forceinline__ void band_step(const KVRegs& r, const bf16x8 (&bq)[NQ][2], LAS unsigned char* vl, int lane, int s, int q0, int W, float (&m)[NQ], float (&l)[NQ], f32x4 (&o)[NQ][4]) {
;     ...
;     for (int g = 0; g < NQ; ++g) {
;         const int qlo = q0 + 16 * g;
;         if (32 * s <= qlo + 15 && 32 * s + 31 >= qlo - W) {
;             f32x4 sa = (f32x4){0.f, 0.f, 0.f, 0.f}, sb = (f32x4){0.f, 0.f, 0.f, 0.f};
;             sa = MFMA16(r.ka[0], bq[g][0], sa); sa = MFMA16(r.ka[1], bq[g][1], sa);
;             sb = MFMA16(r.kb[0], bq[g][0], sb); sb = MFMA16(r.kb[1], bq[g][1], sb);
;             const BandMask mask{32 * s, qlo + qi, W};
;             float x[8];
; #pragma unroll
;             for (int e = 0; e < 4; ++e) { x[e] = mask(4 * g4 + e, sa[e]); x[4 + e] = mask(16 + 4 * g4 + e, sb[e]); }
;             float tm = fmaxf(fmaxf(fmaxf(x[0], x[1]), fmaxf(x[2], x[3])), fmaxf(fmaxf(x[4], x[5]), fmaxf(x[6], x[7])));
;             tm = xmax32(xmax16(tm));
;             const float mn = fmaxf(m[g], tm);
;             if (__ballot(mn > m[g])) { const float al = fast_exp2(m[g] - mn); l[g] *= al;
; #pragma unroll
;                 for (int db = 0; db < 4; ++db) o[g][db] = o[g][db] * al; }
.LBB0_1217:
	s_cmp_gt_i32 s42, s47
	s_cselect_b64 s[4:5], -1, 0
	s_cmp_lt_i32 s2, s48
	s_cselect_b64 s[6:7], -1, 0
	s_or_b64 s[4:5], s[4:5], s[6:7]
	v_subrev_u32_e32 v234, 32, v222
	v_subrev_u32_e32 v229, 33, v222
	v_subrev_u32_e32 v226, 34, v222
	v_subrev_u32_e32 v221, 35, v222
	s_and_b64 vcc, exec, s[4:5]
	v_cmp_ge_u32_e64 s[10:11], s23, v234
	v_cmp_ge_u32_e64 s[8:9], s23, v229
	v_cmp_ge_u32_e64 s[6:7], s23, v226
	v_cmp_ge_u32_e64 s[4:5], s23, v221
	s_cbranch_vccnz .LBB0_1221
	s_waitcnt vmcnt(8)
	v_mfma_f32_16x16x32_bf16 v[190:193], v[126:129], v[58:61], 0
	v_cmp_ge_u32_e32 vcc, s23, v230
	s_waitcnt vmcnt(8)
	v_mfma_f32_16x16x32_bf16 v[186:189], v[118:121], v[58:61], 0
	v_mfma_f32_16x16x32_bf16 v[190:193], v[122:125], v[62:65], v[190:193]
	v_mfma_f32_16x16x32_bf16 v[186:189], v[114:117], v[62:65], v[186:189]
	s_nop 6
	v_cndmask_b32_e32 v235, v233, v190, vcc
	v_cmp_ge_u32_e32 vcc, s23, v228
	v_cndmask_b32_e64 v238, v233, v186, s[10:11]
	v_cndmask_b32_e64 v239, v233, v187, s[8:9]
	v_cndmask_b32_e32 v230, v233, v191, vcc
	v_cmp_ge_u32_e32 vcc, s23, v224
	v_cndmask_b32_e64 v237, v233, v188, s[6:7]
	v_cndmask_b32_e64 v236, v233, v189, s[4:5]
	v_cndmask_b32_e32 v228, v233, v192, vcc
	v_cmp_ge_u32_e32 vcc, s23, v223
	v_max_f32_e32 v186, v239, v239
	v_max_f32_e32 v187, v238, v238
	v_cndmask_b32_e32 v223, v233, v193, vcc
	v_max_f32_e32 v186, v187, v186
	v_max_f32_e32 v187, v236, v236
	v_max_f32_e32 v188, v237, v237
	v_max_f32_e32 v187, v188, v187
	v_max_f32_e32 v188, v223, v223
	v_max_f32_e32 v189, v228, v228
	v_max_f32_e32 v188, v189, v188
	v_max3_f32 v188, v235, v230, v188
	v_max3_f32 v186, v186, v187, v188
	v_mov_b32_e32 v187, v186
	s_nop 1
	v_permlane16_swap_b32_e32 v186, v187
	v_max_f32_e32 v187, v187, v187
	v_max_f32_e32 v186, v186, v186
	v_max_f32_e32 v186, v186, v187
	v_mov_b32_e32 v187, v186
	s_nop 1
	v_permlane32_swap_b32_e32 v186, v187
	v_max3_f32 v224, v220, v186, v187
	v_cmp_gt_f32_e32 vcc, v224, v220
	s_cbranch_vccz .LBB0_1220
	v_sub_f32_e32 v186, v220, v224
	v_exp_f32_e32 v186, v186
	s_nop 0
	v_mul_f32_e32 v207, v207, v186
	v_pk_mul_f32 v[48:49], v[48:49], v[186:187] op_sel_hi:[1,0]
	v_pk_mul_f32 v[46:47], v[46:47], v[186:187] op_sel_hi:[1,0]
	v_pk_mul_f32 v[44:45], v[44:45], v[186:187] op_sel_hi:[1,0]
	v_pk_mul_f32 v[42:43], v[42:43], v[186:187] op_sel_hi:[1,0]
	v_pk_mul_f32 v[40:41], v[40:41], v[186:187] op_sel_hi:[1,0]
	v_pk_mul_f32 v[38:39], v[38:39], v[186:187] op_sel_hi:[1,0]
	v_pk_mul_f32 v[36:37], v[36:37], v[186:187] op_sel_hi:[1,0]
	v_pk_mul_f32 v[34:35], v[34:35], v[186:187] op_sel_hi:[1,0]

; __device__ __forceinline__ float fast_exp2(float x) { return __builtin_amdgcn_exp2f(x); }
; __device__ __forceinline__ float xmax16(float v) { const auto r = __builtin_amdgcn_permlane16_swap(__float_as_uint(v), __float_as_uint(v), false, false); return fmaxf(__uint_as_float(r[0]), __uint_as_float(r[1])); }
; __device__ __forceinline__ float xmax32(float v) { const auto r = __builtin_amdgcn_permlane32_swap(__float_as_uint(v), __float_as_uint(v), false, false); return fmaxf(__uint_as_float(r[0]), __uint_as_float(r[1])); }
; #define MFMA16(a, b, c) __builtin_amdgcn_mfma_f32_16x16x32_bf16((a), (b), (c), 0, 0, 0)
; template <int NQ>
; __device__ __forceinline__ void band_step(const KVRegs& r, const bf16x8 (&bq)[NQ][2], LAS unsigned char* vl, int lane, int s, int q0, int W, float (&m)[NQ], float (&l)[NQ], f32x4 (&o)[NQ][4]) {
;     ...
;     for (int g = 0; g < NQ; ++g) {
;         const int qlo = q0 + 16 * g;
;         if (32 * s <= qlo + 15 && 32 * s + 31 >= qlo - W) {
;             f32x4 sa = (f32x4){0.f, 0.f, 0.f, 0.f}, sb = (f32x4){0.f, 0.f, 0.f, 0.f};
;             sa = MFMA16(r.ka[0], bq[g][0], sa); sa = MFMA16(r.ka[1], bq[g][1], sa);
;             sb = MFMA16(r.kb[0], bq[g][0], sb); sb = MFMA16(r.kb[1], bq[g][1], sb);
;             const BandMask mask{32 * s, qlo + qi, W};
;             float x[8];
; #pragma unroll
;             for (int e = 0; e < 4; ++e) { x[e] = mask(4 * g4 + e, sa[e]); x[4 + e] = mask(16 + 4 * g4 + e, sb[e]); }
;             float tm = fmaxf(fmaxf(fmaxf(x[0], x[1]), fmaxf(x[2], x[3])), fmaxf(fmaxf(x[4], x[5]), fmaxf(x[6], x[7])));
;             tm = xmax32(xmax16(tm));
;             const float mn = fmaxf(m[g], tm);
;             if (__ballot(mn > m[g])) { const float al = fast_exp2(m[g] - mn); l[g] *= al;
; #pragma unroll
;                 for (int db = 0; db < 4; ++db) o[g][db] = o[g][db] * al; }
.LBB0_1222:
	s_cmp_gt_i32 s42, s49
	s_cselect_b64 s[4:5], -1, 0
	s_cmp_lt_i32 s2, s50
	s_cselect_b64 s[6:7], -1, 0
	s_or_b64 s[4:5], s[4:5], s[6:7]
	v_add_u32_e32 v235, -16, v222
	v_subrev_u32_e32 v230, 17, v222
	v_subrev_u32_e32 v228, 18, v222
	v_subrev_u32_e32 v220, 19, v222
	s_and_b64 vcc, exec, s[4:5]
	v_cmp_ge_u32_e64 s[10:11], s23, v235
	v_cmp_ge_u32_e64 s[8:9], s23, v230
	v_cmp_ge_u32_e64 s[6:7], s23, v228
	v_cmp_ge_u32_e64 s[4:5], s23, v220
	s_cbranch_vccnz .LBB0_1226
	s_waitcnt vmcnt(8)
	v_mfma_f32_16x16x32_bf16 v[190:193], v[126:129], v[66:69], 0
	v_cmp_ge_u32_e32 vcc, s23, v234
	s_waitcnt vmcnt(8)
	v_mfma_f32_16x16x32_bf16 v[186:189], v[118:121], v[66:69], 0
	v_mfma_f32_16x16x32_bf16 v[190:193], v[122:125], v[70:73], v[190:193]
	v_mfma_f32_16x16x32_bf16 v[186:189], v[114:117], v[70:73], v[186:189]
	s_nop 6
	v_cndmask_b32_e32 v234, v233, v190, vcc
	v_cmp_ge_u32_e32 vcc, s23, v229
	v_cndmask_b32_e64 v238, v233, v186, s[10:11]
	v_cndmask_b32_e64 v239, v233, v187, s[8:9]
	v_cndmask_b32_e32 v229, v233, v191, vcc
	v_cmp_ge_u32_e32 vcc, s23, v226
	v_cndmask_b32_e64 v237, v233, v188, s[6:7]
	v_cndmask_b32_e64 v236, v233, v189, s[4:5]
	v_cndmask_b32_e32 v226, v233, v192, vcc
	v_cmp_ge_u32_e32 vcc, s23, v221
	v_max_f32_e32 v186, v239, v239
	v_max_f32_e32 v187, v238, v238
	v_cndmask_b32_e32 v221, v233, v193, vcc
	v_max_f32_e32 v186, v187, v186
	v_max_f32_e32 v187, v236, v236
	v_max_f32_e32 v188, v237, v237
	v_max_f32_e32 v187, v188, v187
	v_max_f32_e32 v188, v221, v221
	v_max_f32_e32 v189, v226, v226
	v_max_f32_e32 v188, v189, v188
	v_max3_f32 v188, v234, v229, v188
	v_max3_f32 v186, v186, v187, v188
	v_mov_b32_e32 v187, v186
	s_nop 1
	v_permlane16_swap_b32_e32 v186, v187
	v_max_f32_e32 v187, v187, v187
	v_max_f32_e32 v186, v186, v186
	v_max_f32_e32 v186, v186, v187
	v_mov_b32_e32 v187, v186
	s_nop 1
	v_permlane32_swap_b32_e32 v186, v187
	v_max3_f32 v223, v219, v186, v187
	v_cmp_gt_f32_e32 vcc, v223, v219
	s_cbranch_vccz .LBB0_1225
	v_sub_f32_e32 v186, v219, v223
	v_exp_f32_e32 v186, v186
	s_nop 0
	v_mul_f32_e32 v206, v206, v186
	v_pk_mul_f32 v[32:33], v[32:33], v[186:187] op_sel_hi:[1,0]
	v_pk_mul_f32 v[30:31], v[30:31], v[186:187] op_sel_hi:[1,0]
	v_pk_mul_f32 v[28:29], v[28:29], v[186:187] op_sel_hi:[1,0]
	v_pk_mul_f32 v[26:27], v[26:27], v[186:187] op_sel_hi:[1,0]
	v_pk_mul_f32 v[24:25], v[24:25], v[186:187] op_sel_hi:[1,0]
	v_pk_mul_f32 v[22:23], v[22:23], v[186:187] op_sel_hi:[1,0]
	v_pk_mul_f32 v[20:21], v[20:21], v[186:187] op_sel_hi:[1,0]
	v_pk_mul_f32 v[18:19], v[18:19], v[186:187] op_sel_hi:[1,0]

; __device__ __forceinline__ float fast_exp2(float x) { return __builtin_amdgcn_exp2f(x); }
; __device__ __forceinline__ float xmax16(float v) { const auto r = __builtin_amdgcn_permlane16_swap(__float_as_uint(v), __float_as_uint(v), false, false); return fmaxf(__uint_as_float(r[0]), __uint_as_float(r[1])); }
; __device__ __forceinline__ float xmax32(float v) { const auto r = __builtin_amdgcn_permlane32_swap(__float_as_uint(v), __float_as_uint(v), false, false); return fmaxf(__uint_as_float(r[0]), __uint_as_float(r[1])); }
; #define MFMA16(a, b, c) __builtin_amdgcn_mfma_f32_16x16x32_bf16((a), (b), (c), 0, 0, 0)
; template <int NQ>
; __device__ __forceinline__ void band_step(const KVRegs& r, const bf16x8 (&bq)[NQ][2], LAS unsigned char* vl, int lane, int s, int q0, int W, float (&m)[NQ], float (&l)[NQ], f32x4 (&o)[NQ][4]) {
;     ...
;     for (int g = 0; g < NQ; ++g) {
;         const int qlo = q0 + 16 * g;
;         if (32 * s <= qlo + 15 && 32 * s + 31 >= qlo - W) {
;             f32x4 sa = (f32x4){0.f, 0.f, 0.f, 0.f}, sb = (f32x4){0.f, 0.f, 0.f, 0.f};
;             sa = MFMA16(r.ka[0], bq[g][0], sa); sa = MFMA16(r.ka[1], bq[g][1], sa);
;             sb = MFMA16(r.kb[0], bq[g][0], sb); sb = MFMA16(r.kb[1], bq[g][1], sb);
;             const BandMask mask{32 * s, qlo + qi, W};
;             float x[8];
; #pragma unroll
;             for (int e = 0; e < 4; ++e) { x[e] = mask(4 * g4 + e, sa[e]); x[4 + e] = mask(16 + 4 * g4 + e, sb[e]); }
;             float tm = fmaxf(fmaxf(fmaxf(x[0], x[1]), fmaxf(x[2], x[3])), fmaxf(fmaxf(x[4], x[5]), fmaxf(x[6], x[7])));
;             tm = xmax32(xmax16(tm));
;             const float mn = fmaxf(m[g], tm);
;             if (__ballot(mn > m[g])) { const float al = fast_exp2(m[g] - mn); l[g] *= al;
; #pragma unroll
;                 for (int db = 0; db < 4; ++db) o[g][db] = o[g][db] * al; }
.LBB0_1227:
	s_cmp_gt_i32 s42, s51
	s_cselect_b64 s[4:5], -1, 0
	s_cmp_lt_i32 s2, s52
	s_cselect_b64 s[6:7], -1, 0
	s_or_b64 s[4:5], s[4:5], s[6:7]
	s_and_b64 vcc, exec, s[4:5]
	s_cbranch_vccnz .LBB0_1232
	s_waitcnt vmcnt(8)
	v_mfma_f32_16x16x32_bf16 v[186:189], v[118:121], v[74:77], 0
	v_cmp_ge_u32_e32 vcc, s23, v222
	v_mfma_f32_16x16x32_bf16 v[190:193], v[126:129], v[74:77], 0
	v_mfma_f32_16x16x32_bf16 v[186:189], v[114:117], v[78:81], v[186:189]
	v_mfma_f32_16x16x32_bf16 v[190:193], v[122:125], v[78:81], v[190:193]
	s_nop 6
	v_cndmask_b32_e32 v234, v233, v186, vcc
	v_cmp_ge_u32_e32 vcc, s23, v235
	v_add_u32_e32 v186, -1, v222
	s_nop 0
	v_cndmask_b32_e32 v229, v233, v190, vcc
	v_cmp_ge_u32_e32 vcc, s23, v186
	v_add_u32_e32 v186, -2, v222
	s_nop 0
	v_cndmask_b32_e32 v235, v233, v187, vcc
	v_cmp_ge_u32_e32 vcc, s23, v230
	v_max_f32_e32 v187, v234, v234
	s_nop 0
	v_cndmask_b32_e32 v226, v233, v191, vcc
	v_cmp_ge_u32_e32 vcc, s23, v186
	v_add_u32_e32 v186, -3, v222
	s_nop 0
	v_cndmask_b32_e32 v230, v233, v188, vcc
	v_cmp_ge_u32_e32 vcc, s23, v228
	v_max_f32_e32 v188, v230, v230
	s_nop 0
	v_cndmask_b32_e32 v221, v233, v192, vcc
	v_cmp_ge_u32_e32 vcc, s23, v186
	v_max_f32_e32 v186, v235, v235
	v_max_f32_e32 v186, v187, v186
	v_cndmask_b32_e32 v228, v233, v189, vcc
	v_cmp_ge_u32_e32 vcc, s23, v220
	v_max_f32_e32 v187, v228, v228
	v_max_f32_e32 v187, v188, v187
	v_cndmask_b32_e32 v219, v233, v193, vcc
	v_max_f32_e32 v188, v219, v219
	v_max_f32_e32 v189, v221, v221
	v_max_f32_e32 v188, v189, v188
	v_max3_f32 v188, v229, v226, v188
	v_max3_f32 v186, v186, v187, v188
	v_mov_b32_e32 v187, v186
	s_nop 1
	v_permlane16_swap_b32_e32 v186, v187
	v_max_f32_e32 v187, v187, v187
	v_max_f32_e32 v186, v186, v186
	v_max_f32_e32 v186, v186, v187
	v_mov_b32_e32 v187, v186
	s_nop 1
	v_permlane32_swap_b32_e32 v186, v187
	v_max3_f32 v222, v218, v186, v187
	v_cmp_gt_f32_e32 vcc, v222, v218
	s_cbranch_vccz .LBB0_1230
	v_sub_f32_e32 v186, v218, v222
	v_exp_f32_e32 v186, v186
	s_nop 0
	v_mul_f32_e32 v195, v195, v186
	v_pk_mul_f32 v[16:17], v[16:17], v[186:187] op_sel_hi:[1,0]
	v_pk_mul_f32 v[14:15], v[14:15], v[186:187] op_sel_hi:[1,0]
	v_pk_mul_f32 v[12:13], v[12:13], v[186:187] op_sel_hi:[1,0]
	v_pk_mul_f32 v[10:11], v[10:11], v[186:187] op_sel_hi:[1,0]
	v_pk_mul_f32 v[8:9], v[8:9], v[186:187] op_sel_hi:[1,0]
	v_pk_mul_f32 v[6:7], v[6:7], v[186:187] op_sel_hi:[1,0]
	v_pk_mul_f32 v[4:5], v[4:5], v[186:187] op_sel_hi:[1,0]
	v_pk_mul_f32 v[2:3], v[2:3], v[186:187] op_sel_hi:[1,0]

; __device__ __forceinline__ void kv_load(KVRegs& r, const bf16_t* kbase, size_t kst, const bf16_t* vbase, int s, int lane) {
;     const int li = lane & 15, g4 = lane >> 4;
;     const bf16_t* k0 = kbase + (size_t)(32 * s + li) * kst + 8 * g4;
;     r.ka[0] = *(const bf16x8*)k0; r.ka[1] = *(const bf16x8*)(k0 + 32);
;     const bf16_t* k1 = k0 + 16 * kst;
;     r.kb[0] = *(const bf16x8*)k1; r.kb[1] = *(const bf16x8*)(k1 + 32);
;     const bf16_t* vp = vbase + (size_t)(32 * s + (lane >> 1)) * kst + (lane & 1) * 32;
; #pragma unroll
;     for (int i = 0; i < 4; ++i) r.v[i] = *(const u32x4*)(vp + 8 * i);
; }
; template <int NQ>
; __device__ __forceinline__ void band_unit(int u, const bf16_t* P, bf16_t* OB, bf16_t* ACX, float* LSE, const float* sink, LAS unsigned char* vl, int lane_in) {
;     ...
;     for (int s = s_lo; s <= s_hi; s += RING) {
; #pragma unroll
;         for (int j = 0; j < RING; ++j) {
;             if (s + j <= s_hi) {
;                 if (s + j + RING - 1 <= s_hi) kv_load(kv[(j + RING - 1) % RING], kbase, kst, vbase, s + j + RING - 1, lane);
;                 band_step<NQ>(kv[j], bq, vl, lane, s + j, q0, W, m, l, o);
.LBB0_1233:
	s_or_b32 s2, s42, 32
	s_cmp_ge_i32 s40, s26
	s_cbranch_scc1 .LBB0_1235
	s_add_i32 s0, s2, 32
	v_or_b32_e32 v98, s0, v210
	v_mad_i64_i32 v[98:99], s[4:5], s41, v98, 0
	v_lshl_add_u64 v[98:99], v[98:99], 1, v[196:197]
	global_load_dwordx4 v[118:121], v[98:99], off
	global_load_dwordx4 v[114:117], v[98:99], off offset:64
	v_lshl_add_u64 v[98:99], v[98:99], 0, s[54:55]
	global_load_dwordx4 v[126:129], v[98:99], off
	global_load_dwordx4 v[122:125], v[98:99], off offset:64
	v_add_u32_e32 v98, s0, v211
	v_mad_i64_i32 v[98:99], s[4:5], s41, v98, 0
	v_lshl_add_u64 v[110:111], v[98:99], 1, v[198:199]
	global_load_dwordx4 v[98:101], v[110:111], off offset:48
	global_load_dwordx4 v[102:105], v[110:111], off offset:32
	global_load_dwordx4 v[106:109], v[110:111], off offset:16
	s_nop 0
	global_load_dwordx4 v[110:113], v[110:111], off
	s_waitcnt vmcnt(8)
	s_branch .Lband_bodyB

; #define LAS __attribute__((address_space(3)))
; __device__ __forceinline__ float fast_exp2(float x) { return __builtin_amdgcn_exp2f(x); }
; __device__ __forceinline__ float xmax16(float v) { const auto r = __builtin_amdgcn_permlane16_swap(__float_as_uint(v), __float_as_uint(v), false, false); return fmaxf(__uint_as_float(r[0]), __uint_as_float(r[1])); }
; __device__ __forceinline__ float xmax32(float v) { const auto r = __builtin_amdgcn_permlane32_swap(__float_as_uint(v), __float_as_uint(v), false, false); return fmaxf(__uint_as_float(r[0]), __uint_as_float(r[1])); }
; template <int NQ>
; __device__ __forceinline__ void band_step(const KVRegs& r, const bf16x8 (&bq)[NQ][2], LAS unsigned char* vl, int lane, int s, int q0, int W, float (&m)[NQ], float (&l)[NQ], f32x4 (&o)[NQ][4]) {
;     ...
;     { LAS unsigned char* wp = vl + (lane >> 1) * 128 + (lane & 1) * 64;
; #pragma unroll
;       for (int i = 0; i < 4; ++i) *(LAS u32x4*)(wp + 16 * i) = r.v[i]; }
;     asm volatile("s_waitcnt lgkmcnt(0)" ::: "memory");
;     bf16x8 vf[4];
;     { LAS unsigned char* rd = vl + (4 * g4 + (qi >> 2)) * 128 + (lane & 3) * 8;
; #pragma unroll
;       for (int db = 0; db < 4; ++db) { const s16x4 t0 = tr_read(rd + db * 32), t1 = tr_read(rd + 16 * 128 + db * 32);
;           vf[db] = (bf16x8){t0[0], t0[1], t0[2], t0[3], t1[0], t1[1], t1[2], t1[3]}; } }
; #pragma unroll
;     for (int g = 0; g < NQ; ++g) {
;         const int qlo = q0 + 16 * g;
;         if (32 * s <= qlo + 15 && 32 * s + 31 >= qlo - W) {
;             f32x4 sa = (f32x4){0.f, 0.f, 0.f, 0.f}, sb = (f32x4){0.f, 0.f, 0.f, 0.f};
;             sa = MFMA16(r.ka[0], bq[g][0], sa); sa = MFMA16(r.ka[1], bq[g][1], sa);
;             sb = MFMA16(r.kb[0], bq[g][0], sb); sb = MFMA16(r.kb[1], bq[g][1], sb);
;             const BandMask mask{32 * s, qlo + qi, W};
;             float x[8];
; #pragma unroll
;             for (int e = 0; e < 4; ++e) { x[e] = mask(4 * g4 + e, sa[e]); x[4 + e] = mask(16 + 4 * g4 + e, sb[e]); }
;             float tm = fmaxf(fmaxf(fmaxf(x[0], x[1]), fmaxf(x[2], x[3])), fmaxf(fmaxf(x[4], x[5]), fmaxf(x[6], x[7])));
;             tm = xmax32(xmax16(tm));
;             const float mn = fmaxf(m[g], tm);
;             if (__ballot(mn > m[g])) { const float al = fast_exp2(m[g] - mn); l[g] *= al;
; #pragma unroll
;                 for (int db = 0; db < 4; ++db) o[g][db] = o[g][db] * al; }
.Lband_bodyB:
	ds_write_b128 v0, v[158:161]
	ds_write_b128 v0, v[154:157] offset:16
	ds_write_b128 v0, v[142:145] offset:32
	ds_write_b128 v0, v[138:141] offset:48
	s_waitcnt lgkmcnt(0)
	s_waitcnt lgkmcnt(11)
	ds_read_b64_tr_b16 v[174:175], v216
	s_waitcnt lgkmcnt(11)
	ds_read_b64_tr_b16 v[170:171], v216 offset:32
	s_waitcnt lgkmcnt(9)
	ds_read_b64_tr_b16 v[166:167], v216 offset:64
	s_waitcnt lgkmcnt(8)
	ds_read_b64_tr_b16 v[162:163], v216 offset:96
	ds_read_b64_tr_b16 v[176:177], v216 offset:2048
	ds_read_b64_tr_b16 v[172:173], v216 offset:2080
	ds_read_b64_tr_b16 v[168:169], v216 offset:2112
	s_waitcnt lgkmcnt(11)
	ds_read_b64_tr_b16 v[164:165], v216 offset:2144
	s_or_b32 s4, s42, 63
	s_cmp_gt_i32 s2, s43
	s_cselect_b64 s[6:7], -1, 0
	s_cmp_lt_i32 s4, s46
	s_cselect_b64 s[8:9], -1, 0
	s_or_b64 s[6:7], s[6:7], s[8:9]
	v_add_u32_e32 v218, s2, v212
	s_and_b64 vcc, exec, s[6:7]
	s_cbranch_vccnz .LBB0_1239
	v_mfma_f32_16x16x32_bf16 v[186:189], v[134:137], v[50:53], 0
	v_sub_u32_e32 v219, v194, v218
	v_add_u32_e32 v220, -16, v219
	v_cmp_ge_u32_e32 vcc, s23, v219
	v_mfma_f32_16x16x32_bf16 v[190:193], v[150:153], v[50:53], 0
	v_mfma_f32_16x16x32_bf16 v[186:189], v[130:133], v[54:57], v[186:189]
	v_mfma_f32_16x16x32_bf16 v[190:193], v[146:149], v[54:57], v[190:193]
	s_nop 6
	v_cndmask_b32_e32 v229, v233, v186, vcc
	v_cmp_ge_u32_e32 vcc, s23, v220
	v_add_u32_e32 v186, -1, v219
	s_nop 0
	v_cndmask_b32_e32 v228, v233, v190, vcc
	v_cmp_ge_u32_e32 vcc, s23, v186
	v_subrev_u32_e32 v186, 17, v219
	s_nop 0
	v_cndmask_b32_e32 v235, v233, v187, vcc
	v_cmp_ge_u32_e32 vcc, s23, v186
	v_add_u32_e32 v186, -2, v219
	v_max_f32_e32 v187, v229, v229
	v_cndmask_b32_e32 v226, v233, v191, vcc
	v_cmp_ge_u32_e32 vcc, s23, v186
	v_subrev_u32_e32 v186, 18, v219
	s_nop 0
	v_cndmask_b32_e32 v234, v233, v188, vcc
	v_cmp_ge_u32_e32 vcc, s23, v186
	v_add_u32_e32 v186, -3, v219
	v_max_f32_e32 v188, v234, v234
	v_cndmask_b32_e32 v220, v233, v192, vcc
	v_cmp_ge_u32_e32 vcc, s23, v186
	v_subrev_u32_e32 v186, 19, v219
	s_nop 0
	v_cndmask_b32_e32 v230, v233, v189, vcc
	v_cmp_ge_u32_e32 vcc, s23, v186
	v_max_f32_e32 v186, v235, v235
	v_max_f32_e32 v186, v187, v186
	v_cndmask_b32_e32 v219, v233, v193, vcc
	v_max_f32_e32 v187, v230, v230
	v_max_f32_e32 v187, v188, v187
	v_max_f32_e32 v188, v219, v219
	v_max_f32_e32 v189, v220, v220
	v_max_f32_e32 v188, v189, v188
	v_max3_f32 v188, v228, v226, v188
	v_max3_f32 v186, v186, v187, v188
	v_mov_b32_e32 v187, v186
	s_nop 1
	v_permlane16_swap_b32_e32 v186, v187
	v_max_f32_e32 v187, v187, v187
	v_max_f32_e32 v186, v186, v186
	v_max_f32_e32 v186, v186, v187
	v_mov_b32_e32 v187, v186
	s_nop 1
	v_permlane32_swap_b32_e32 v186, v187
	v_max3_f32 v221, v225, v186, v187
	v_cmp_gt_f32_e32 vcc, v221, v225
	s_cbranch_vccz .LBB0_1238
	v_sub_f32_e32 v186, v225, v221
	v_exp_f32_e32 v186, v186
	s_nop 0
	v_mul_f32_e32 v209, v209, v186
	v_pk_mul_f32 v[96:97], v[96:97], v[186:187] op_sel_hi:[1,0]
	v_pk_mul_f32 v[94:95], v[94:95], v[186:187] op_sel_hi:[1,0]
	v_pk_mul_f32 v[92:93], v[92:93], v[186:187] op_sel_hi:[1,0]
	v_pk_mul_f32 v[90:91], v[90:91], v[186:187] op_sel_hi:[1,0]
	v_pk_mul_f32 v[88:89], v[88:89], v[186:187] op_sel_hi:[1,0]
	v_pk_mul_f32 v[86:87], v[86:87], v[186:187] op_sel_hi:[1,0]
	v_pk_mul_f32 v[84:85], v[84:85], v[186:187] op_sel_hi:[1,0]
	v_pk_mul_f32 v[82:83], v[82:83], v[186:187] op_sel_hi:[1,0]

; __device__ __forceinline__ float xsum16(float v) { const auto r = __builtin_amdgcn_permlane16_swap(__float_as_uint(v), __float_as_uint(v), false, false); return __uint_as_float(r[0]) + __uint_as_float(r[1]); }
; __device__ __forceinline__ float xsum32(float v) { const auto r = __builtin_amdgcn_permlane32_swap(__float_as_uint(v), __float_as_uint(v), false, false); return __uint_as_float(r[0]) + __uint_as_float(r[1]); }
; __device__ __forceinline__ void row_stats4(const float* st, int rowb, int fq, float (&mu)[4], float (&rs)[4]) {
;     f32x4 a[4], b[4];
; #pragma unroll
;     for (int m = 0; m < 4; ++m) { const f32x4* p = (const f32x4*)(st + (size_t)(rowb + m * 16) * 32 + fq * 8); a[m] = p[0]; b[m] = p[1]; }
; #pragma unroll
;     for (int m = 0; m < 4; ++m) { float s1 = (a[m][0] + a[m][2]) + (b[m][0] + b[m][2]), s2 = (a[m][1] + a[m][3]) + (b[m][1] + b[m][3]);
;         s1 = xsum32(xsum16(s1)); s2 = xsum32(xsum16(s2));
;         const float mm = s1 * (1.0f / 1024.0f); mu[m] = mm; rs[m] = rsqrtf(fmaxf(s2 * (1.0f / 1024.0f) - mm * mm, 0.f) + LN_EPS_); }
;     __device__ __forceinline__ void operator()(const f32x4 (&acc)[2][2][4][2], const pg8::Unit& u, int wr, int wc, int fr, int fq) const {
;     ...
;         for (int ai = 0; ai < 2; ++ai) { float mu4[4], rs4[4]; row_stats4(stp, row0 + ai * 128, fq, mu4, rs4);
; #pragma unroll
;             for (int m = 0; m < 4; ++m) { const int row = row0 + ai * 128 + m * 16; const float mu = mu4[m], rs = rs4[m];
;                 f32x4 yv[2][2], gq[2][2], bq_[2][2];
; #pragma unroll
;                 for (int bj = 0; bj < 2; ++bj)
; #pragma unroll
;                     for (int n = 0; n < 2; ++n) { yv[bj][n] = *(const f32x4*)(Yin + (size_t)row * D_ + col0 + bj * 128 + 4 * n); gq[bj][n] = *(const f32x4*)(g + col0 + bj * 128 + 4 * n); bq_[bj][n] = *(const f32x4*)(b + col0 + bj * 128 + 4 * n); }
;                 asm volatile("" ::: "memory");
.LBB0_1535:
	s_lshl_b32 s3, s3, 8
	s_add_i32 s3, s3, s0
	v_or_b32_e32 v158, s3, v184
	v_ashrrev_i32_e32 v159, 31, v158
	v_lshlrev_b64 v[130:131], 7, v[158:159]
	v_lshl_add_u64 v[136:137], v[146:147], 0, v[130:131]
	v_or_b32_e32 v180, 16, v158
	global_load_dwordx4 v[132:135], v[136:137], off
	global_load_dwordx4 v[166:169], v[136:137], off offset:16
	v_ashrrev_i32_e32 v181, 31, v180
	v_lshlrev_b64 v[172:173], 7, v[180:181]
	v_lshl_add_u64 v[136:137], v[146:147], 0, v[172:173]
	global_load_dwordx4 v[174:177], v[136:137], off
	global_load_dwordx4 v[186:189], v[136:137], off offset:16
	v_or_b32_e32 v170, 32, v158
	v_ashrrev_i32_e32 v171, 31, v170
	v_lshlrev_b64 v[164:165], 7, v[170:171]
	v_lshl_add_u64 v[136:137], v[146:147], 0, v[164:165]
	global_load_dwordx4 v[190:193], v[136:137], off
	global_load_dwordx4 v[198:201], v[136:137], off offset:16
	v_or_b32_e32 v162, 48, v158
	v_ashrrev_i32_e32 v163, 31, v162
	v_lshlrev_b64 v[160:161], 7, v[162:163]
	v_lshl_add_u64 v[182:183], v[146:147], 0, v[160:161]
	global_load_dwordx4 v[202:205], v[182:183], off
	global_load_dwordx4 v[206:209], v[182:183], off offset:16
	s_load_dwordx16 s[64:79], s[34:35], 0x38
	s_lshl_b32 s1, s2, 8
	s_lshl_b32 s14, s2, 3
	s_or_b32 s2, s1, s57
	v_or_b32_e32 v152, s2, v185
	v_ashrrev_i32_e32 v153, 31, v152
	v_lshlrev_b64 v[136:137], 12, v[158:159]
	v_lshlrev_b64 v[178:179], 2, v[152:153]
	s_waitcnt lgkmcnt(0)
	v_lshl_add_u64 v[136:137], s[78:79], 0, v[136:137]
	v_lshl_add_u64 v[156:157], s[8:9], 0, v[178:179]
	v_lshl_add_u64 v[154:155], s[10:11], 0, v[178:179]
	v_lshl_add_u64 v[136:137], v[136:137], 0, v[178:179]
	s_or_b32 s52, s14, s61
	s_mov_b32 s14, 0x3a800000
	global_load_dwordx4 v[210:213], v[136:137], off offset:16
	global_load_dwordx4 v[214:217], v[136:137], off
	global_load_dwordx4 v[218:221], v[156:157], off offset:16
	global_load_dwordx4 v[222:225], v[156:157], off
	global_load_dwordx4 v[234:237], v[154:155], off offset:16
	global_load_dwordx4 v[238:241], v[154:155], off
	s_mov_b32 s98, 0x10000
	s_mov_b32 s99, 0
	v_lshl_add_u64 v[242:243], v[136:137], 0, s[98:99]
	global_load_dword v0, v[242:243], off
	global_load_dword v0, v[242:243], off offset:512
	v_lshl_add_u64 v[242:243], v[242:243], 0, s[98:99]
	global_load_dword v0, v[242:243], off
	global_load_dword v0, v[242:243], off offset:512
	v_lshl_add_u64 v[242:243], v[242:243], 0, s[98:99]
	global_load_dword v0, v[242:243], off
	global_load_dword v0, v[242:243], off offset:512
	s_mov_b32 s98, 0x50000
	v_lshl_add_u64 v[242:243], v[242:243], 0, s[98:99]
	s_mov_b32 s98, 0x10000
	global_load_dword v0, v[242:243], off
	global_load_dword v0, v[242:243], off offset:512
	v_lshl_add_u64 v[242:243], v[242:243], 0, s[98:99]
	global_load_dword v0, v[242:243], off
	global_load_dword v0, v[242:243], off offset:512
	v_lshl_add_u64 v[242:243], v[242:243], 0, s[98:99]
	global_load_dword v0, v[242:243], off
	global_load_dword v0, v[242:243], off offset:512
	v_lshl_add_u64 v[242:243], v[242:243], 0, s[98:99]
	global_load_dword v0, v[242:243], off
	global_load_dword v0, v[242:243], off offset:512
	s_mov_b32 s1, 0x800000
	s_mov_b32 s18, 0x3fd744fd
	v_bitop3_b32 v196, s2, 56, v185 bitop3:0xc8
	s_ashr_i32 s2, s2, 6
	s_ashr_i32 s53, s52, 31
	v_readlane_b32 s16, v253, 59
	v_readlane_b32 s17, v253, 60
	s_waitcnt vmcnt(0)
	v_mov_b32_e32 v178, v132
	v_mov_b32_e32 v179, v166
	v_mov_b32_e32 v182, v134
	v_mov_b32_e32 v183, v168
	v_mov_b32_e32 v166, v133
	v_mov_b32_e32 v168, v135
	v_pk_add_f32 v[132:133], v[178:179], v[182:183]
	v_pk_add_f32 v[134:135], v[166:167], v[168:169]
	v_pk_add_f32 v[132:133], v[132:133], v[132:133] op_sel:[0,1] op_sel_hi:[1,0]
	v_pk_add_f32 v[134:135], v[134:135], v[134:135] op_sel:[0,1] op_sel_hi:[1,0]
	v_mov_b32_e32 v166, v174
	v_mov_b32_e32 v167, v186
	v_mov_b32_e32 v168, v176
	v_mov_b32_e32 v169, v188
	v_mov_b32_e32 v0, v132
	v_mov_b32_e32 v133, v134
	v_pk_add_f32 v[166:167], v[166:167], v[168:169]
	v_permlane16_swap_b32_e32 v132, v0
	v_permlane16_swap_b32_e32 v134, v133
	v_mov_b32_e32 v188, v177
	v_pk_add_f32 v[166:167], v[166:167], v[166:167] op_sel:[0,1] op_sel_hi:[1,0]
	v_add_f32_e32 v177, v132, v0
	v_add_f32_e32 v176, v134, v133
	v_mov_b32_e32 v135, v166
	v_mov_b32_e32 v179, v177
	v_mov_b32_e32 v178, v176
	v_permlane16_swap_b32_e32 v166, v135
	v_permlane32_swap_b32_e32 v177, v179
	v_permlane32_swap_b32_e32 v176, v178
	v_mov_b32_e32 v186, v175
	v_add_f32_e32 v133, v166, v135
	v_pk_add_f32 v[166:167], v[176:177], v[178:179]
	v_pk_add_f32 v[168:169], v[186:187], v[188:189]
	v_pk_mul_f32 v[178:179], v[166:167], s[14:15] op_sel_hi:[1,0]
	v_pk_add_f32 v[168:169], v[168:169], v[168:169] op_sel:[0,1] op_sel_hi:[1,0]
	v_fma_f32 v0, -v179, v179, v178
	v_mov_b32_e32 v159, v168
	v_max_f32_e32 v0, 0, v0
	s_nop 0
	v_permlane16_swap_b32_e32 v168, v159
	v_add_f32_e32 v0, 0x3727c5ac, v0
	v_add_f32_e32 v132, v168, v159
	v_mul_f32_e32 v159, 0x4b800000, v0
	v_cmp_gt_f32_e32 vcc, s1, v0
	v_mov_b32_e32 v174, v190
	v_mov_b32_e32 v175, v198
	v_cndmask_b32_e32 v0, v0, v159, vcc
	v_rsq_f32_e32 v0, v0
	v_mov_b32_e32 v166, v192
	v_mov_b32_e32 v167, v200
	v_pk_add_f32 v[166:167], v[174:175], v[166:167]
	v_mul_f32_e32 v159, 0x45800000, v0
	v_pk_add_f32 v[166:167], v[166:167], v[166:167] op_sel:[0,1] op_sel_hi:[1,0]
	v_mov_b32_e32 v198, v191
	v_mov_b32_e32 v200, v193
	v_cndmask_b32_e32 v0, v0, v159, vcc
	v_pk_add_f32 v[168:169], v[198:199], v[200:201]
	v_mov_b32_e32 v159, v166
	v_pk_add_f32 v[168:169], v[168:169], v[168:169] op_sel:[0,1] op_sel_hi:[1,0]
	s_nop 0
	v_permlane16_swap_b32_e32 v166, v159
	v_add_f32_e32 v175, v166, v159
	v_mov_b32_e32 v159, v168
	s_nop 1
	v_permlane16_swap_b32_e32 v168, v159
	global_load_dwordx4 v[186:189], v[136:137], off offset:528
; __device__ __forceinline__ float xsum16(float v) { const auto r = __builtin_amdgcn_permlane16_swap(__float_as_uint(v), __float_as_uint(v), false, false); return __uint_as_float(r[0]) + __uint_as_float(r[1]); }
; __device__ __forceinline__ float xsum32(float v) { const auto r = __builtin_amdgcn_permlane32_swap(__float_as_uint(v), __float_as_uint(v), false, false); return __uint_as_float(r[0]) + __uint_as_float(r[1]); }
; __device__ __forceinline__ size_t blk_off(int r, int c, int K) { return (size_t)(r >> 8) * 256 * K + (size_t)(c >> 6) * (256 * 64) + (size_t)((r & 255) * 64 + (c & 63)); }
; __device__ __forceinline__ u32x4 pack8(const f32x4 a, const f32x4 b) { u32x4 w; w.x = cvt_pk_bf16(a[0], a[1]); w.y = cvt_pk_bf16(a[2], a[3]); w.z = cvt_pk_bf16(b[0], b[1]); w.w = cvt_pk_bf16(b[2], b[3]); return w; }
;     __device__ __forceinline__ void operator()(const f32x4 (&acc)[2][2][4][2], const pg8::Unit& u, int wr, int wc, int fr, int fq) const {
;     ...
;                 float s1 = 0.f, s2 = 0.f;
; #pragma unroll
;                 for (int bj = 0; bj < 2; ++bj) { float* yp = Y + (size_t)row * D_ + col0 + bj * 128; f32x4 v[2];
; #pragma unroll
;                     for (int n = 0; n < 2; ++n) { v[n] = (((yv[bj][n] - mu) * rs) * gq[bj][n] + bq_[bj][n]) * ALPHA_ + acc[ai][bj][m][n] * sc;
;                         *(f32x4*)(yp + 4 * n) = v[n]; s1 += (v[n][0] + v[n][1]) + (v[n][2] + v[n][3]); s2 += (v[n][0] * v[n][0] + v[n][1] * v[n][1]) + (v[n][2] * v[n][2] + v[n][3] * v[n][3]); }
;                     *(u32x4*)(Yb + blk_off(row, col0 + bj * 128, D_)) = pack8(v[0], v[1]); }
;                 s1 = xsum32(xsum16(s1)); s2 = xsum32(xsum16(s2));
;                 if (fq == 0) *(f32x2*)(stn + (size_t)row * 32 + (u.pn * 4 + wc) * 2) = (f32x2){s1, s2}; asm volatile("" ::: "memory"); } }
	global_load_dwordx4 v[190:193], v[136:137], off offset:512
	v_add_f32_e32 v174, v168, v159
	v_mov_b32_e32 v166, v202
	v_mov_b32_e32 v167, v206
	v_mov_b32_e32 v168, v204
	v_mov_b32_e32 v169, v208
	v_mov_b32_e32 v206, v203
	v_mov_b32_e32 v208, v205
	v_pk_add_f32 v[166:167], v[166:167], v[168:169]
	v_pk_add_f32 v[168:169], v[206:207], v[208:209]
	global_load_dwordx4 v[198:201], v[156:157], off offset:528
	global_load_dwordx4 v[202:205], v[156:157], off offset:512
	global_load_dwordx4 v[206:209], v[154:155], off offset:528
	global_load_dwordx4 v[242:245], v[154:155], off offset:512
	v_sub_f32_e32 v183, v215, v179
	v_sub_f32_e32 v182, v214, v179
	v_sub_f32_e32 v215, v217, v179
	v_sub_f32_e32 v214, v216, v179
	v_pk_mul_f32 v[214:215], v[0:1], v[214:215] op_sel_hi:[0,1]
	v_pk_mul_f32 v[182:183], v[0:1], v[182:183] op_sel_hi:[0,1]
	v_pk_fma_f32 v[182:183], v[222:223], v[182:183], v[238:239]
	v_pk_fma_f32 v[214:215], v[224:225], v[214:215], v[240:241]
	v_pk_fma_f32 v[126:127], v[182:183], s[18:19], v[126:127] op_sel_hi:[1,0,1]
	v_pk_fma_f32 v[128:129], v[214:215], s[18:19], v[128:129] op_sel_hi:[1,0,1]
	v_add_f32_e32 v178, v126, v127
	v_add_f32_e32 v182, v128, v129
	v_add_f32_e32 v178, v178, v182
	v_mul_f32_e32 v182, v127, v127
	v_mul_f32_e32 v183, v129, v129
	v_fmac_f32_e32 v182, v126, v126
	v_fmac_f32_e32 v183, v128, v128
	v_add_f32_e32 v197, v182, v183
	v_sub_f32_e32 v183, v211, v179
	v_sub_f32_e32 v182, v210, v179
	v_sub_f32_e32 v211, v213, v179
	v_sub_f32_e32 v210, v212, v179
	v_pk_mul_f32 v[210:211], v[0:1], v[210:211] op_sel_hi:[0,1]
	v_pk_mul_f32 v[182:183], v[0:1], v[182:183] op_sel_hi:[0,1]
	v_pk_fma_f32 v[182:183], v[218:219], v[182:183], v[234:235]
	v_pk_fma_f32 v[210:211], v[220:221], v[210:211], v[236:237]
	v_pk_add_f32 v[166:167], v[166:167], v[166:167] op_sel:[0,1] op_sel_hi:[1,0]
	v_pk_fma_f32 v[124:125], v[210:211], s[18:19], v[124:125] op_sel_hi:[1,0,1]
	v_pk_fma_f32 v[122:123], v[182:183], s[18:19], v[122:123] op_sel_hi:[1,0,1]
	v_mov_b32_e32 v159, v166
	v_add_f32_e32 v182, v122, v123
	v_add_f32_e32 v183, v124, v125
	v_pk_add_f32 v[168:169], v[168:169], v[168:169] op_sel:[0,1] op_sel_hi:[1,0]
	v_permlane16_swap_b32_e32 v166, v159
	v_add_f32_e32 v178, 0, v178
	v_add_f32_e32 v182, v182, v183
	v_add_f32_e32 v167, v166, v159
	v_mov_b32_e32 v159, v168
	s_ashr_i32 s14, s3, 8
	v_add_f32_e32 v178, v178, v182
	v_mul_f32_e32 v182, v123, v123
	v_mul_f32_e32 v183, v125, v125
	v_permlane16_swap_b32_e32 v168, v159
	s_ashr_i32 s15, s14, 31
	global_store_dwordx4 v[136:137], v[126:129], off
	global_store_dwordx4 v[136:137], v[122:125], off offset:16
	v_fmac_f32_e32 v182, v122, v122
	v_fmac_f32_e32 v183, v124, v124
	v_cvt_pk_bf16_f32 v126, v126, v127
	v_cvt_pk_bf16_f32 v127, v128, v129
	v_cvt_pk_bf16_f32 v128, v122, v123
	v_cvt_pk_bf16_f32 v129, v124, v125
	v_add_f32_e32 v166, v168, v159
	s_lshl_b64 s[14:15], s[14:15], 19
	v_lshlrev_b32_e32 v159, 6, v158
	s_movk_i32 s1, 0x33c0
	s_ashr_i32 s3, s2, 31
	v_and_or_b32 v159, v159, s1, v196
	s_add_u32 s1, s16, s14
	s_addc_u32 s14, s17, s15
	s_lshl_b64 s[24:25], s[2:3], 15
	s_add_u32 s42, s1, s24
	s_addc_u32 s43, s14, s25
	v_lshlrev_b32_e32 v159, 1, v159
	global_store_dwordx4 v159, v[126:129], s[42:43]
	v_add_f32_e32 v182, v182, v183
	s_waitcnt vmcnt(7)
	v_sub_f32_e32 v123, v191, v179
	v_sub_f32_e32 v122, v190, v179
	v_sub_f32_e32 v125, v193, v179
	v_sub_f32_e32 v124, v192, v179
	v_pk_mul_f32 v[124:125], v[0:1], v[124:125] op_sel_hi:[0,1]
	v_pk_mul_f32 v[122:123], v[0:1], v[122:123] op_sel_hi:[0,1]
	v_add_f32_e32 v182, v197, v182
	s_or_b32 s2, s2, 2
	s_ashr_i32 s3, s2, 31
	s_lshl_b64 s[28:29], s[2:3], 15
	s_waitcnt vmcnt(3)
	v_pk_fma_f32 v[122:123], v[202:203], v[122:123], v[242:243]
	v_pk_fma_f32 v[124:125], v[204:205], v[124:125], v[244:245]
	v_pk_fma_f32 v[118:119], v[122:123], s[18:19], v[118:119] op_sel_hi:[1,0,1]
	v_pk_fma_f32 v[120:121], v[124:125], s[18:19], v[120:121] op_sel_hi:[1,0,1]
	v_add_f32_e32 v122, v118, v119
	v_add_f32_e32 v123, v120, v121
	v_add_f32_e32 v122, v122, v123
	v_add_f32_e32 v126, v178, v122
	v_mul_f32_e32 v122, v119, v119
	v_mul_f32_e32 v123, v121, v121
	v_fmac_f32_e32 v122, v118, v118
	v_fmac_f32_e32 v123, v120, v120
	v_add_f32_e32 v122, v122, v123
	v_add_f32_e32 v127, v182, v122
	v_sub_f32_e32 v123, v187, v179
	v_sub_f32_e32 v122, v186, v179
	v_sub_f32_e32 v125, v189, v179
	v_sub_f32_e32 v124, v188, v179
	v_pk_mul_f32 v[124:125], v[0:1], v[124:125] op_sel_hi:[0,1]
	v_pk_mul_f32 v[122:123], v[0:1], v[122:123] op_sel_hi:[0,1]
	v_pk_fma_f32 v[122:123], v[198:199], v[122:123], v[206:207]
	v_pk_fma_f32 v[124:125], v[200:201], v[124:125], v[208:209]
	v_pk_fma_f32 v[114:115], v[122:123], s[18:19], v[114:115] op_sel_hi:[1,0,1]
	v_pk_fma_f32 v[116:117], v[124:125], s[18:19], v[116:117] op_sel_hi:[1,0,1]
	v_add_f32_e32 v0, v114, v115
	v_add_f32_e32 v122, v116, v117
	v_add_f32_e32 v0, v0, v122
	v_mul_f32_e32 v122, v115, v115
	v_mul_f32_e32 v123, v117, v117
	v_add_f32_e32 v0, v126, v0
	v_fmac_f32_e32 v122, v114, v114
	v_fmac_f32_e32 v123, v116, v116
	global_store_dwordx4 v[136:137], v[118:121], off offset:512
	global_store_dwordx4 v[136:137], v[114:117], off offset:528
	v_add_f32_e32 v122, v122, v123
	v_cvt_pk_bf16_f32 v118, v118, v119
	v_cvt_pk_bf16_f32 v119, v120, v121
	v_cvt_pk_bf16_f32 v120, v114, v115
	v_mov_b32_e32 v114, v0
	v_add_f32_e32 v122, v127, v122
	s_nop 0
	v_permlane16_swap_b32_e32 v0, v114
	v_add_f32_e32 v114, v0, v114
	v_mov_b32_e32 v0, v122
	s_nop 1
	v_permlane16_swap_b32_e32 v122, v0
	v_add_f32_e32 v115, v122, v0
	v_mov_b32_e32 v135, v133
	v_mov_b32_e32 v134, v132
	v_mov_b32_e32 v177, v175
	v_mov_b32_e32 v176, v174
	v_mov_b32_e32 v169, v167
	v_mov_b32_e32 v168, v166
	v_cvt_pk_bf16_f32 v121, v116, v117
	s_add_u32 s40, s1, s28
	v_mov_b32_e32 v116, v114
	v_mov_b32_e32 v117, v115
	v_permlane32_swap_b32_e32 v133, v135
	v_permlane32_swap_b32_e32 v132, v134
	v_permlane32_swap_b32_e32 v175, v177
	v_permlane32_swap_b32_e32 v174, v176
	v_permlane32_swap_b32_e32 v167, v169
	v_permlane32_swap_b32_e32 v166, v168
	s_addc_u32 s41, s14, s29
	v_permlane32_swap_b32_e32 v114, v116
	v_permlane32_swap_b32_e32 v115, v117
	global_store_dwordx4 v159, v[118:121], s[40:41]
	s_and_saveexec_b64 s[26:27], s[44:45]
	s_cbranch_execz .LBB0_1537
	v_pk_add_f32 v[114:115], v[114:115], v[116:117]
	v_lshl_add_u64 v[116:117], s[6:7], 0, v[130:131]
	v_lshl_add_u64 v[116:117], s[52:53], 2, v[116:117]
	global_store_dwordx2 v[116:117], v[114:115], off

; __device__ __forceinline__ float xsum16(float v) { const auto r = __builtin_amdgcn_permlane16_swap(__float_as_uint(v), __float_as_uint(v), false, false); return __uint_as_float(r[0]) + __uint_as_float(r[1]); }
; __device__ __forceinline__ float xsum32(float v) { const auto r = __builtin_amdgcn_permlane32_swap(__float_as_uint(v), __float_as_uint(v), false, false); return __uint_as_float(r[0]) + __uint_as_float(r[1]); }
; __device__ __forceinline__ void row_stats4(const float* st, int rowb, int fq, float (&mu)[4], float (&rs)[4]) {
;     f32x4 a[4], b[4];
; #pragma unroll
;     for (int m = 0; m < 4; ++m) { const f32x4* p = (const f32x4*)(st + (size_t)(rowb + m * 16) * 32 + fq * 8); a[m] = p[0]; b[m] = p[1]; }
; #pragma unroll
;     for (int m = 0; m < 4; ++m) { float s1 = (a[m][0] + a[m][2]) + (b[m][0] + b[m][2]), s2 = (a[m][1] + a[m][3]) + (b[m][1] + b[m][3]);
;         s1 = xsum32(xsum16(s1)); s2 = xsum32(xsum16(s2));
;         const float mm = s1 * (1.0f / 1024.0f); mu[m] = mm; rs[m] = rsqrtf(fmaxf(s2 * (1.0f / 1024.0f) - mm * mm, 0.f) + LN_EPS_); }
;     __device__ __forceinline__ void operator()(const f32x4 (&acc)[2][2][4][2], const pg8::Unit& u, int wr, int wc, int fr, int fq) const {
;     ...
;         for (int ai = 0; ai < 2; ++ai) { float mu4[4], rs4[4]; row_stats4(stp, row0 + ai * 128, fq, mu4, rs4);
; #pragma unroll
;             for (int m = 0; m < 4; ++m) { const int row = row0 + ai * 128 + m * 16; const float mu = mu4[m], rs = rs4[m];
;                 f32x4 yv[2][2], gq[2][2], bq_[2][2];
; #pragma unroll
;                 for (int bj = 0; bj < 2; ++bj)
; #pragma unroll
;                     for (int n = 0; n < 2; ++n) { yv[bj][n] = *(const f32x4*)(Yin + (size_t)row * D_ + col0 + bj * 128 + 4 * n); gq[bj][n] = *(const f32x4*)(g + col0 + bj * 128 + 4 * n); bq_[bj][n] = *(const f32x4*)(b + col0 + bj * 128 + 4 * n); }
;                 asm volatile("" ::: "memory");
.LBB0_1703:
	s_lshl_b32 s3, s3, 8
	s_add_i32 s3, s3, s0
	v_or_b32_e32 v158, s3, v184
	v_ashrrev_i32_e32 v159, 31, v158
	v_lshlrev_b64 v[130:131], 7, v[158:159]
	v_lshl_add_u64 v[136:137], v[146:147], 0, v[130:131]
	v_or_b32_e32 v182, 16, v158
	global_load_dwordx4 v[132:135], v[136:137], off
	global_load_dwordx4 v[166:169], v[136:137], off offset:16
	v_ashrrev_i32_e32 v183, 31, v182
	v_lshlrev_b64 v[172:173], 7, v[182:183]
	v_lshl_add_u64 v[136:137], v[146:147], 0, v[172:173]
	global_load_dwordx4 v[174:177], v[136:137], off
	global_load_dwordx4 v[178:181], v[136:137], off offset:16
	v_or_b32_e32 v170, 32, v158
	v_ashrrev_i32_e32 v171, 31, v170
	v_lshlrev_b64 v[164:165], 7, v[170:171]
	v_lshl_add_u64 v[136:137], v[146:147], 0, v[164:165]
	global_load_dwordx4 v[186:189], v[136:137], off
	global_load_dwordx4 v[190:193], v[136:137], off offset:16
	s_load_dwordx16 s[60:75], s[34:35], 0x38
	s_lshl_b32 s1, s2, 8
	s_lshl_b32 s16, s2, 3
	s_or_b32 s2, s1, s53
	v_or_b32_e32 v162, 48, v158
	v_or_b32_e32 v152, s2, v185
	v_ashrrev_i32_e32 v163, 31, v162
	v_ashrrev_i32_e32 v153, 31, v152
	v_lshlrev_b64 v[136:137], 12, v[158:159]
	v_lshlrev_b64 v[160:161], 7, v[162:163]
	v_lshlrev_b64 v[198:199], 2, v[152:153]
	s_waitcnt lgkmcnt(0)
	v_lshl_add_u64 v[136:137], s[74:75], 0, v[136:137]
	v_lshl_add_u64 v[202:203], v[146:147], 0, v[160:161]
	v_lshl_add_u64 v[156:157], s[10:11], 0, v[198:199]
	v_lshl_add_u64 v[154:155], s[12:13], 0, v[198:199]
	v_lshl_add_u64 v[136:137], v[136:137], 0, v[198:199]
	global_load_dwordx4 v[198:201], v[202:203], off
	s_nop 0
	global_load_dwordx4 v[202:205], v[202:203], off offset:16
	s_or_b32 s38, s16, s15
	s_mov_b32 s16, 0x3a800000
	s_mov_b32 s1, 0x800000
	global_load_dwordx4 v[206:209], v[136:137], off offset:16
	global_load_dwordx4 v[210:213], v[136:137], off
	global_load_dwordx4 v[214:217], v[156:157], off offset:16
	global_load_dwordx4 v[218:221], v[156:157], off
	global_load_dwordx4 v[222:225], v[154:155], off offset:16
	global_load_dwordx4 v[234:237], v[154:155], off
	s_mov_b32 s98, 0x10000
	s_mov_b32 s99, 0
	v_lshl_add_u64 v[228:229], v[136:137], 0, s[98:99]
	global_load_dword v0, v[228:229], off
	global_load_dword v0, v[228:229], off offset:512
	v_lshl_add_u64 v[228:229], v[228:229], 0, s[98:99]
	global_load_dword v0, v[228:229], off
	global_load_dword v0, v[228:229], off offset:512
	v_lshl_add_u64 v[228:229], v[228:229], 0, s[98:99]
	global_load_dword v0, v[228:229], off
	global_load_dword v0, v[228:229], off offset:512
	s_mov_b32 s98, 0x50000
	v_lshl_add_u64 v[228:229], v[228:229], 0, s[98:99]
	s_mov_b32 s98, 0x10000
	global_load_dword v0, v[228:229], off
	global_load_dword v0, v[228:229], off offset:512
	v_lshl_add_u64 v[228:229], v[228:229], 0, s[98:99]
	global_load_dword v0, v[228:229], off
	global_load_dword v0, v[228:229], off offset:512
	v_lshl_add_u64 v[228:229], v[228:229], 0, s[98:99]
	global_load_dword v0, v[228:229], off
	global_load_dword v0, v[228:229], off offset:512
	v_lshl_add_u64 v[228:229], v[228:229], 0, s[98:99]
	global_load_dword v0, v[228:229], off
	global_load_dword v0, v[228:229], off offset:512
	s_mov_b32 s18, 0x3fd744fd
	s_ashr_i32 s44, s2, 6
	v_bitop3_b32 v196, s2, 56, v185 bitop3:0xc8
	s_ashr_i32 s39, s38, 31
	s_ashr_i32 s45, s44, 31
	s_waitcnt vmcnt(0)
	v_mov_b32_e32 v228, v132
	v_mov_b32_e32 v229, v166
	v_mov_b32_e32 v238, v134
	v_mov_b32_e32 v239, v168
	v_mov_b32_e32 v166, v133
	v_mov_b32_e32 v168, v135
	v_pk_add_f32 v[132:133], v[228:229], v[238:239]
	v_pk_add_f32 v[134:135], v[166:167], v[168:169]
	v_pk_add_f32 v[132:133], v[132:133], v[132:133] op_sel:[0,1] op_sel_hi:[1,0]
	v_pk_add_f32 v[134:135], v[134:135], v[134:135] op_sel:[0,1] op_sel_hi:[1,0]
	v_mov_b32_e32 v166, v174
	v_mov_b32_e32 v167, v178
	v_mov_b32_e32 v168, v176
	v_mov_b32_e32 v169, v180
	v_mov_b32_e32 v0, v132
	v_mov_b32_e32 v133, v134
	v_pk_add_f32 v[166:167], v[166:167], v[168:169]
	v_permlane16_swap_b32_e32 v132, v0
	v_permlane16_swap_b32_e32 v134, v133
	v_mov_b32_e32 v178, v175
	v_mov_b32_e32 v180, v177
	v_pk_add_f32 v[166:167], v[166:167], v[166:167] op_sel:[0,1] op_sel_hi:[1,0]
	v_add_f32_e32 v177, v132, v0
	v_add_f32_e32 v176, v134, v133
	v_pk_add_f32 v[168:169], v[178:179], v[180:181]
	v_mov_b32_e32 v135, v166
	v_mov_b32_e32 v179, v177
	v_mov_b32_e32 v178, v176
	v_permlane16_swap_b32_e32 v166, v135
	v_permlane32_swap_b32_e32 v177, v179
	v_permlane32_swap_b32_e32 v176, v178
	v_add_f32_e32 v133, v166, v135
	v_pk_add_f32 v[166:167], v[176:177], v[178:179]
	v_pk_add_f32 v[168:169], v[168:169], v[168:169] op_sel:[0,1] op_sel_hi:[1,0]
	v_pk_mul_f32 v[228:229], v[166:167], s[16:17] op_sel_hi:[1,0]
	v_mov_b32_e32 v159, v168
	v_fma_f32 v0, -v229, v229, v228
	v_max_f32_e32 v0, 0, v0
	v_permlane16_swap_b32_e32 v168, v159
	v_add_f32_e32 v0, 0x3727c5ac, v0
	v_add_f32_e32 v132, v168, v159
	v_mul_f32_e32 v159, 0x4b800000, v0
	v_cmp_gt_f32_e32 vcc, s1, v0
	v_mov_b32_e32 v174, v186
	v_mov_b32_e32 v175, v190
	v_cndmask_b32_e32 v0, v0, v159, vcc
	v_rsq_f32_e32 v0, v0
	v_mov_b32_e32 v166, v188
	v_mov_b32_e32 v167, v192
	v_pk_add_f32 v[166:167], v[174:175], v[166:167]
	v_mul_f32_e32 v159, 0x45800000, v0
	v_pk_add_f32 v[166:167], v[166:167], v[166:167] op_sel:[0,1] op_sel_hi:[1,0]
	v_mov_b32_e32 v190, v187
	v_mov_b32_e32 v192, v189
	v_cndmask_b32_e32 v0, v0, v159, vcc
	v_pk_add_f32 v[168:169], v[190:191], v[192:193]
	v_mov_b32_e32 v159, v166
	v_pk_add_f32 v[168:169], v[168:169], v[168:169] op_sel:[0,1] op_sel_hi:[1,0]
	s_nop 0
	v_permlane16_swap_b32_e32 v166, v159
	v_add_f32_e32 v175, v166, v159
	v_mov_b32_e32 v159, v168
	s_nop 1
	v_permlane16_swap_b32_e32 v168, v159
	global_load_dwordx4 v[178:181], v[136:137], off offset:528
; __device__ __forceinline__ float xsum16(float v) { const auto r = __builtin_amdgcn_permlane16_swap(__float_as_uint(v), __float_as_uint(v), false, false); return __uint_as_float(r[0]) + __uint_as_float(r[1]); }
; __device__ __forceinline__ float xsum32(float v) { const auto r = __builtin_amdgcn_permlane32_swap(__float_as_uint(v), __float_as_uint(v), false, false); return __uint_as_float(r[0]) + __uint_as_float(r[1]); }
; __device__ __forceinline__ size_t blk_off(int r, int c, int K) { return (size_t)(r >> 8) * 256 * K + (size_t)(c >> 6) * (256 * 64) + (size_t)((r & 255) * 64 + (c & 63)); }
; __device__ __forceinline__ u32x4 pack8(const f32x4 a, const f32x4 b) { u32x4 w; w.x = cvt_pk_bf16(a[0], a[1]); w.y = cvt_pk_bf16(a[2], a[3]); w.z = cvt_pk_bf16(b[0], b[1]); w.w = cvt_pk_bf16(b[2], b[3]); return w; }
;     __device__ __forceinline__ void operator()(const f32x4 (&acc)[2][2][4][2], const pg8::Unit& u, int wr, int wc, int fr, int fq) const {
;     ...
;                 float s1 = 0.f, s2 = 0.f;
; #pragma unroll
;                 for (int bj = 0; bj < 2; ++bj) { float* yp = Y + (size_t)row * D_ + col0 + bj * 128; f32x4 v[2];
; #pragma unroll
;                     for (int n = 0; n < 2; ++n) { v[n] = (((yv[bj][n] - mu) * rs) * gq[bj][n] + bq_[bj][n]) * ALPHA_ + acc[ai][bj][m][n] * sc;
;                         *(f32x4*)(yp + 4 * n) = v[n]; s1 += (v[n][0] + v[n][1]) + (v[n][2] + v[n][3]); s2 += (v[n][0] * v[n][0] + v[n][1] * v[n][1]) + (v[n][2] * v[n][2] + v[n][3] * v[n][3]); }
;                     *(u32x4*)(Yb + blk_off(row, col0 + bj * 128, D_)) = pack8(v[0], v[1]); }
;                 s1 = xsum32(xsum16(s1)); s2 = xsum32(xsum16(s2));
;                 if (fq == 0) *(f32x2*)(stn + (size_t)row * 32 + (u.pn * 4 + wc) * 2) = (f32x2){s1, s2}; asm volatile("" ::: "memory"); } }
	global_load_dwordx4 v[186:189], v[136:137], off offset:512
	v_add_f32_e32 v174, v168, v159
	v_mov_b32_e32 v166, v198
	v_mov_b32_e32 v167, v202
	v_mov_b32_e32 v168, v200
	v_mov_b32_e32 v169, v204
	v_mov_b32_e32 v202, v199
	v_mov_b32_e32 v204, v201
	v_pk_add_f32 v[166:167], v[166:167], v[168:169]
	v_pk_add_f32 v[168:169], v[202:203], v[204:205]
	global_load_dwordx4 v[190:193], v[156:157], off offset:528
	global_load_dwordx4 v[198:201], v[156:157], off offset:512
	global_load_dwordx4 v[202:205], v[154:155], off offset:528
	global_load_dwordx4 v[238:241], v[154:155], off offset:512
	v_sub_f32_e32 v213, v213, v229
	v_sub_f32_e32 v212, v212, v229
	v_sub_f32_e32 v211, v211, v229
	v_sub_f32_e32 v210, v210, v229
	v_pk_mul_f32 v[210:211], v[0:1], v[210:211] op_sel_hi:[0,1]
	v_pk_mul_f32 v[212:213], v[0:1], v[212:213] op_sel_hi:[0,1]
	v_sub_f32_e32 v209, v209, v229
	v_sub_f32_e32 v208, v208, v229
	v_sub_f32_e32 v207, v207, v229
	v_sub_f32_e32 v206, v206, v229
	v_pk_fma_f32 v[212:213], v[220:221], v[212:213], v[236:237]
	v_pk_fma_f32 v[210:211], v[218:219], v[210:211], v[234:235]
	v_pk_mul_f32 v[206:207], v[0:1], v[206:207] op_sel_hi:[0,1]
	v_pk_mul_f32 v[208:209], v[0:1], v[208:209] op_sel_hi:[0,1]
	v_pk_mul_f32 v[210:211], v[210:211], s[18:19] op_sel_hi:[1,0]
	v_pk_mul_f32 v[212:213], v[212:213], s[18:19] op_sel_hi:[1,0]
	v_pk_fma_f32 v[208:209], v[216:217], v[208:209], v[224:225]
	v_pk_fma_f32 v[206:207], v[214:215], v[206:207], v[222:223]
	v_pk_fma_f32 v[128:129], v[128:129], 0.5, v[212:213] op_sel_hi:[1,0,1]
	v_pk_fma_f32 v[126:127], v[126:127], 0.5, v[210:211] op_sel_hi:[1,0,1]
	v_pk_mul_f32 v[206:207], v[206:207], s[18:19] op_sel_hi:[1,0]
	v_pk_mul_f32 v[208:209], v[208:209], s[18:19] op_sel_hi:[1,0]
	v_add_f32_e32 v197, v126, v127
	v_add_f32_e32 v210, v128, v129
	v_pk_fma_f32 v[124:125], v[124:125], 0.5, v[208:209] op_sel_hi:[1,0,1]
	v_pk_fma_f32 v[122:123], v[122:123], 0.5, v[206:207] op_sel_hi:[1,0,1]
	v_pk_add_f32 v[166:167], v[166:167], v[166:167] op_sel:[0,1] op_sel_hi:[1,0]
	v_add_f32_e32 v197, v197, v210
	v_add_f32_e32 v206, v122, v123
	v_add_f32_e32 v207, v124, v125
	v_mov_b32_e32 v159, v166
	v_add_f32_e32 v197, 0, v197
	v_add_f32_e32 v206, v206, v207
	v_pk_add_f32 v[168:169], v[168:169], v[168:169] op_sel:[0,1] op_sel_hi:[1,0]
	v_permlane16_swap_b32_e32 v166, v159
	v_mul_f32_e32 v210, v127, v127
	v_mul_f32_e32 v211, v129, v129
	v_add_f32_e32 v197, v197, v206
	v_mul_f32_e32 v206, v123, v123
	v_mul_f32_e32 v207, v125, v125
	v_add_f32_e32 v167, v166, v159
	v_mov_b32_e32 v159, v168
	s_ashr_i32 s16, s3, 8
	global_store_dwordx4 v[136:137], v[126:129], off
	v_fmac_f32_e32 v210, v126, v126
	v_fmac_f32_e32 v211, v128, v128
	global_store_dwordx4 v[136:137], v[122:125], off offset:16
	v_fmac_f32_e32 v206, v122, v122
	v_fmac_f32_e32 v207, v124, v124
	v_cvt_pk_bf16_f32 v126, v126, v127
	v_cvt_pk_bf16_f32 v127, v128, v129
	v_cvt_pk_bf16_f32 v128, v122, v123
	v_cvt_pk_bf16_f32 v129, v124, v125
	v_permlane16_swap_b32_e32 v168, v159
	s_ashr_i32 s17, s16, 31
	v_add_f32_e32 v166, v168, v159
	s_lshl_b64 s[16:17], s[16:17], 19
	v_lshlrev_b32_e32 v159, 6, v158
	s_movk_i32 s1, 0x33c0
	v_readlane_b32 s2, v253, 59
	v_and_or_b32 v159, v159, s1, v196
	v_readlane_b32 s3, v253, 60
	s_add_u32 s1, s2, s16
	s_addc_u32 s16, s3, s17
	s_lshl_b64 s[24:25], s[44:45], 15
	s_add_u32 s48, s1, s24
	s_waitcnt vmcnt(6)
	v_sub_f32_e32 v123, v189, v229
	v_sub_f32_e32 v122, v188, v229
	v_sub_f32_e32 v125, v187, v229
	v_sub_f32_e32 v124, v186, v229
	v_pk_mul_f32 v[124:125], v[0:1], v[124:125] op_sel_hi:[0,1]
	v_pk_mul_f32 v[122:123], v[0:1], v[122:123] op_sel_hi:[0,1]
	s_addc_u32 s49, s16, s25
	v_lshlrev_b32_e32 v159, 1, v159
	global_store_dwordx4 v159, v[126:129], s[48:49]
	v_add_f32_e32 v210, v210, v211
	s_waitcnt vmcnt(3)
	v_pk_fma_f32 v[122:123], v[200:201], v[122:123], v[240:241]
	v_pk_fma_f32 v[124:125], v[198:199], v[124:125], v[238:239]
	v_pk_mul_f32 v[122:123], v[122:123], s[18:19] op_sel_hi:[1,0]
	v_pk_mul_f32 v[124:125], v[124:125], s[18:19] op_sel_hi:[1,0]
	v_pk_fma_f32 v[120:121], v[120:121], 0.5, v[122:123] op_sel_hi:[1,0,1]
	v_pk_fma_f32 v[118:119], v[118:119], 0.5, v[124:125] op_sel_hi:[1,0,1]
	v_add_f32_e32 v123, v120, v121
	v_add_f32_e32 v122, v118, v119
	v_add_f32_e32 v122, v122, v123
	v_add_f32_e32 v126, v197, v122
	v_mul_f32_e32 v122, v119, v119
	v_mul_f32_e32 v123, v121, v121
	v_add_f32_e32 v206, v206, v207
	v_fmac_f32_e32 v122, v118, v118
	v_fmac_f32_e32 v123, v120, v120
	v_add_f32_e32 v206, v210, v206
	v_add_f32_e32 v122, v122, v123
	v_add_f32_e32 v127, v206, v122
	v_sub_f32_e32 v123, v181, v229
	v_sub_f32_e32 v122, v180, v229
	v_sub_f32_e32 v125, v179, v229
	v_sub_f32_e32 v124, v178, v229
	v_pk_mul_f32 v[124:125], v[0:1], v[124:125] op_sel_hi:[0,1]
	v_pk_mul_f32 v[122:123], v[0:1], v[122:123] op_sel_hi:[0,1]
	v_pk_fma_f32 v[122:123], v[192:193], v[122:123], v[204:205]
	v_pk_fma_f32 v[124:125], v[190:191], v[124:125], v[202:203]
	v_pk_mul_f32 v[122:123], v[122:123], s[18:19] op_sel_hi:[1,0]
	v_pk_mul_f32 v[124:125], v[124:125], s[18:19] op_sel_hi:[1,0]
	v_pk_fma_f32 v[116:117], v[116:117], 0.5, v[122:123] op_sel_hi:[1,0,1]
	v_pk_fma_f32 v[114:115], v[114:115], 0.5, v[124:125] op_sel_hi:[1,0,1]
	v_add_f32_e32 v122, v116, v117
	v_add_f32_e32 v0, v114, v115
	v_add_f32_e32 v0, v0, v122
	v_mul_f32_e32 v122, v115, v115
	v_mul_f32_e32 v123, v117, v117
	v_add_f32_e32 v0, v126, v0
	v_fmac_f32_e32 v122, v114, v114
	v_fmac_f32_e32 v123, v116, v116
	global_store_dwordx4 v[136:137], v[118:121], off offset:512
	global_store_dwordx4 v[136:137], v[114:117], off offset:528
	v_add_f32_e32 v122, v122, v123
	v_cvt_pk_bf16_f32 v118, v118, v119
	v_cvt_pk_bf16_f32 v119, v120, v121
	v_cvt_pk_bf16_f32 v120, v114, v115
	v_mov_b32_e32 v114, v0
	v_add_f32_e32 v122, v127, v122
	s_nop 0
	v_permlane16_swap_b32_e32 v0, v114
	s_or_b32 s2, s44, 2
	v_add_f32_e32 v114, v0, v114
	v_mov_b32_e32 v0, v122
	s_ashr_i32 s3, s2, 31
	s_nop 0
	v_permlane16_swap_b32_e32 v122, v0
	s_lshl_b64 s[44:45], s[2:3], 15
	v_add_f32_e32 v115, v122, v0
	v_mov_b32_e32 v135, v133
	v_mov_b32_e32 v134, v132
	v_mov_b32_e32 v177, v175
	v_mov_b32_e32 v176, v174
	v_mov_b32_e32 v169, v167
	v_mov_b32_e32 v168, v166
	v_cvt_pk_bf16_f32 v121, v116, v117
	s_add_u32 s46, s1, s44
	v_mov_b32_e32 v116, v114
	v_mov_b32_e32 v117, v115
	v_permlane32_swap_b32_e32 v133, v135
	v_permlane32_swap_b32_e32 v132, v134
	v_permlane32_swap_b32_e32 v175, v177
	v_permlane32_swap_b32_e32 v174, v176
	v_permlane32_swap_b32_e32 v167, v169
	v_permlane32_swap_b32_e32 v166, v168
	s_addc_u32 s47, s16, s45
	v_permlane32_swap_b32_e32 v114, v116
	v_permlane32_swap_b32_e32 v115, v117
	global_store_dwordx4 v159, v[118:121], s[46:47]
	s_and_saveexec_b64 s[26:27], s[40:41]
	s_cbranch_execz .LBB0_1705
	v_pk_add_f32 v[114:115], v[114:115], v[116:117]
	v_lshl_add_u64 v[116:117], s[8:9], 0, v[130:131]
	v_lshl_add_u64 v[116:117], s[38:39], 2, v[116:117]
	global_store_dwordx2 v[116:117], v[114:115], off
